# adds rewritten phase-H norm hand-off (non-final layers) and removes the no-op lgkmcnt(0) wait and setprio 0/1 pair inside each GEMM MFMA block head
# speedup vs baseline: 1.0246x; 1.0152x over previous
.LBB0_222:
	s_add_u32 s6, s0, 0xfffc0080
	s_addc_u32 s7, s1, -1
	s_add_i32 s39, 0, 0x10000
	s_cmp_eq_u32 s38, 12
	s_cselect_b32 s7, s8, s7
	s_cselect_b32 s6, s9, s6
	v_add_u32_e32 v0, s39, v173
	s_cselect_b32 s45, s27, s37
	s_cselect_b32 s44, s29, s36
	s_add_i32 s41, 0, 0x14000
	ds_read_b128 v[22:25], v0
	ds_read_b128 v[26:29], v0 offset:1024
	ds_read_b128 v[34:37], v0 offset:2048
	ds_read_b128 v[38:41], v0 offset:3072
	v_add_u32_e32 v0, s41, v173
	ds_read_b128 v[146:149], v0
	ds_read_b128 v[150:153], v0 offset:1024
	ds_read_b128 v[154:157], v0 offset:2048
	ds_read_b128 v[158:161], v0 offset:3072
	v_lshl_add_u64 v[218:219], s[0:1], 0, v[202:203]
	s_add_i32 m0, s2, 0xc000
	ds_read_b128 v[204:207], v209
	ds_read_b128 v[214:217], v209 offset:1024
	ds_read_b128 v[228:231], v209 offset:2048
	ds_read_b128 v[232:235], v209 offset:3072
	ds_read_b128 v[236:239], v209 offset:4096
	ds_read_b128 v[240:243], v209 offset:5120
	ds_read_b128 v[244:247], v209 offset:6144
	ds_read_b128 v[248:251], v209 offset:7168
	global_load_lds_dwordx4 v[218:219], off
	v_lshl_add_u64 v[218:219], v[218:219], 0, s[94:95]
	s_add_i32 m0, s2, 0xe000
	s_nop 0
	global_load_lds_dwordx4 v[218:219], off
	s_waitcnt vmcnt(8)
	s_waitcnt lgkmcnt(0)
	s_barrier
	s_setprio 1
	v_mfma_f32_16x16x32_bf16 v[162:165], v[22:25], v[204:207], v[162:165]
	v_mfma_f32_16x16x32_bf16 v[142:145], v[34:37], v[204:207], v[142:145]
	v_mfma_f32_16x16x32_bf16 v[130:133], v[22:25], v[228:231], v[130:133]
	v_mfma_f32_16x16x32_bf16 v[126:129], v[34:37], v[228:231], v[126:129]
	v_mfma_f32_16x16x32_bf16 v[114:117], v[22:25], v[236:239], v[114:117]
	v_mfma_f32_16x16x32_bf16 v[110:113], v[34:37], v[236:239], v[110:113]
	v_mfma_f32_16x16x32_bf16 v[98:101], v[22:25], v[244:247], v[98:101]
	v_mfma_f32_16x16x32_bf16 v[94:97], v[34:37], v[244:247], v[94:97]
	v_mfma_f32_16x16x32_bf16 v[162:165], v[26:29], v[214:217], v[162:165]
	v_mfma_f32_16x16x32_bf16 v[142:145], v[38:41], v[214:217], v[142:145]
	v_mfma_f32_16x16x32_bf16 v[130:133], v[26:29], v[232:235], v[130:133]
	v_mfma_f32_16x16x32_bf16 v[126:129], v[38:41], v[232:235], v[126:129]
	v_mfma_f32_16x16x32_bf16 v[114:117], v[26:29], v[240:243], v[114:117]
	v_mfma_f32_16x16x32_bf16 v[110:113], v[38:41], v[240:243], v[110:113]
	v_mfma_f32_16x16x32_bf16 v[98:101], v[26:29], v[248:251], v[98:101]
	v_mfma_f32_16x16x32_bf16 v[94:97], v[38:41], v[248:251], v[94:97]
	v_mfma_f32_16x16x32_bf16 v[138:141], v[146:149], v[204:207], v[138:141]
	v_mfma_f32_16x16x32_bf16 v[134:137], v[154:157], v[204:207], v[134:137]
	v_mfma_f32_16x16x32_bf16 v[122:125], v[146:149], v[228:231], v[122:125]
	v_mfma_f32_16x16x32_bf16 v[118:121], v[154:157], v[228:231], v[118:121]
	v_mfma_f32_16x16x32_bf16 v[106:109], v[146:149], v[236:239], v[106:109]
	v_mfma_f32_16x16x32_bf16 v[102:105], v[154:157], v[236:239], v[102:105]
	v_mfma_f32_16x16x32_bf16 v[90:93], v[146:149], v[244:247], v[90:93]
	v_mfma_f32_16x16x32_bf16 v[86:89], v[154:157], v[244:247], v[86:89]
	v_mfma_f32_16x16x32_bf16 v[138:141], v[150:153], v[214:217], v[138:141]
	v_mfma_f32_16x16x32_bf16 v[134:137], v[158:161], v[214:217], v[134:137]
	v_mfma_f32_16x16x32_bf16 v[122:125], v[150:153], v[232:235], v[122:125]
	v_mfma_f32_16x16x32_bf16 v[118:121], v[158:161], v[232:235], v[118:121]
	v_mfma_f32_16x16x32_bf16 v[106:109], v[150:153], v[240:243], v[106:109]
	v_mfma_f32_16x16x32_bf16 v[102:105], v[158:161], v[240:243], v[102:105]
	v_mfma_f32_16x16x32_bf16 v[90:93], v[150:153], v[248:251], v[90:93]
	v_mfma_f32_16x16x32_bf16 v[86:89], v[158:161], v[248:251], v[86:89]
	s_setprio 0
	s_barrier
	s_add_i32 s39, s39, s43
	v_lshl_add_u64 v[218:219], s[44:45], 0, v[166:167]
	s_mov_b32 m0, s39
	ds_read_b128 v[204:207], v209 offset:16384
	ds_read_b128 v[214:217], v209 offset:17408
	ds_read_b128 v[228:231], v209 offset:18432
	ds_read_b128 v[232:235], v209 offset:19456
	ds_read_b128 v[236:239], v209 offset:20480
	ds_read_b128 v[240:243], v209 offset:21504
	ds_read_b128 v[244:247], v209 offset:22528
	ds_read_b128 v[248:251], v209 offset:23552
	global_load_lds_dwordx4 v[218:219], off
	v_lshl_add_u64 v[252:253], v[218:219], 0, s[88:89]
	s_add_i32 m0, s39, 0x2000
	s_add_i32 s39, s41, s43
	global_load_lds_dwordx4 v[252:253], off
	v_lshl_add_u64 v[252:253], v[218:219], 0, s[90:91]
	s_mov_b32 m0, s39
	s_nop 0
	global_load_lds_dwordx4 v[252:253], off
	v_lshl_add_u64 v[252:253], v[218:219], 0, s[92:93]
	s_add_i32 m0, s39, 0x2000
	s_nop 0
	global_load_lds_dwordx4 v[252:253], off
	v_lshl_add_u64 v[252:253], s[6:7], 0, v[168:169]
	s_mov_b32 m0, s2
	v_lshl_add_u64 v[226:227], v[252:253], 0, s[94:95]
	global_load_lds_dwordx4 v[252:253], off
	s_mov_b32 m0, s3
	s_nop 0
	global_load_lds_dwordx4 v[226:227], off
	s_waitcnt vmcnt(8)
	s_waitcnt lgkmcnt(0)
	s_barrier
	s_setprio 1
	v_mfma_f32_16x16x32_bf16 v[82:85], v[22:25], v[204:207], v[82:85]
	v_mfma_f32_16x16x32_bf16 v[78:81], v[34:37], v[204:207], v[78:81]
	v_mfma_f32_16x16x32_bf16 v[66:69], v[22:25], v[228:231], v[66:69]
	v_mfma_f32_16x16x32_bf16 v[62:65], v[34:37], v[228:231], v[62:65]
	v_mfma_f32_16x16x32_bf16 v[50:53], v[22:25], v[236:239], v[50:53]
	v_mfma_f32_16x16x32_bf16 v[46:49], v[34:37], v[236:239], v[46:49]
	v_mfma_f32_16x16x32_bf16 v[18:21], v[22:25], v[244:247], v[18:21]
	v_mfma_f32_16x16x32_bf16 v[14:17], v[34:37], v[244:247], v[14:17]
	v_mfma_f32_16x16x32_bf16 v[82:85], v[26:29], v[214:217], v[82:85]
	v_mfma_f32_16x16x32_bf16 v[78:81], v[38:41], v[214:217], v[78:81]
	v_mfma_f32_16x16x32_bf16 v[66:69], v[26:29], v[232:235], v[66:69]
	v_mfma_f32_16x16x32_bf16 v[62:65], v[38:41], v[232:235], v[62:65]
	v_mfma_f32_16x16x32_bf16 v[50:53], v[26:29], v[240:243], v[50:53]
	v_mfma_f32_16x16x32_bf16 v[46:49], v[38:41], v[240:243], v[46:49]
	v_mfma_f32_16x16x32_bf16 v[18:21], v[26:29], v[248:251], v[18:21]
	v_mfma_f32_16x16x32_bf16 v[14:17], v[38:41], v[248:251], v[14:17]
	v_mfma_f32_16x16x32_bf16 v[42:45], v[146:149], v[236:239], v[42:45]
	v_mfma_f32_16x16x32_bf16 v[30:33], v[154:157], v[236:239], v[30:33]
	v_mfma_f32_16x16x32_bf16 v[10:13], v[146:149], v[244:247], v[10:13]
	v_mfma_f32_16x16x32_bf16 v[6:9], v[154:157], v[244:247], v[6:9]
	v_mfma_f32_16x16x32_bf16 v[22:25], v[146:149], v[204:207], v[74:77]
	v_mfma_f32_16x16x32_bf16 v[26:29], v[154:157], v[204:207], v[70:73]
	v_mfma_f32_16x16x32_bf16 v[34:37], v[146:149], v[228:231], v[58:61]
	v_mfma_f32_16x16x32_bf16 v[38:41], v[154:157], v[228:231], v[54:57]
	v_mfma_f32_16x16x32_bf16 v[42:45], v[150:153], v[240:243], v[42:45]
	v_mfma_f32_16x16x32_bf16 v[30:33], v[158:161], v[240:243], v[30:33]
	v_mfma_f32_16x16x32_bf16 v[10:13], v[150:153], v[248:251], v[10:13]
	v_mfma_f32_16x16x32_bf16 v[6:9], v[158:161], v[248:251], v[6:9]
	v_mfma_f32_16x16x32_bf16 v[22:25], v[150:153], v[214:217], v[22:25]
	v_mfma_f32_16x16x32_bf16 v[26:29], v[158:161], v[214:217], v[26:29]
	v_mfma_f32_16x16x32_bf16 v[34:37], v[150:153], v[232:235], v[34:37]
	v_mfma_f32_16x16x32_bf16 v[38:41], v[158:161], v[232:235], v[38:41]
	s_setprio 0
	s_barrier
	s_add_i32 s6, 0, 0x18000
	v_add_u32_e32 v0, s6, v173
	s_add_i32 s7, 0, 0x1c000
	ds_read_b128 v[54:57], v0
	ds_read_b128 v[58:61], v0 offset:1024
	ds_read_b128 v[70:73], v0 offset:2048
	ds_read_b128 v[74:77], v0 offset:3072
	v_add_u32_e32 v0, s7, v173
	ds_read_b128 v[146:149], v0
	ds_read_b128 v[150:153], v0 offset:1024
	ds_read_b128 v[154:157], v0 offset:2048
	ds_read_b128 v[158:161], v0 offset:3072
	s_mov_b32 m0, s33
	v_lshl_add_u64 v[226:227], v[252:253], 0, s[96:97]
	ds_read_b128 v[204:207], v209 offset:32768
	ds_read_b128 v[214:217], v209 offset:33792
	ds_read_b128 v[228:231], v209 offset:34816
	ds_read_b128 v[232:235], v209 offset:35840
	ds_read_b128 v[236:239], v209 offset:36864
	ds_read_b128 v[240:243], v209 offset:37888
	ds_read_b128 v[244:247], v209 offset:38912
	ds_read_b128 v[248:251], v209 offset:39936
	global_load_lds_dwordx4 v[226:227], off
	v_lshl_add_u64 v[226:227], v[252:253], 0, s[86:87]
	s_mov_b32 m0, s72
	s_nop 0
	global_load_lds_dwordx4 v[226:227], off
	s_waitcnt vmcnt(8)
	s_waitcnt lgkmcnt(0)
	s_barrier
	s_setprio 1
	v_mfma_f32_16x16x32_bf16 v[162:165], v[54:57], v[204:207], v[162:165]
	v_mfma_f32_16x16x32_bf16 v[142:145], v[70:73], v[204:207], v[142:145]
	v_mfma_f32_16x16x32_bf16 v[130:133], v[54:57], v[228:231], v[130:133]
	v_mfma_f32_16x16x32_bf16 v[126:129], v[70:73], v[228:231], v[126:129]
	v_mfma_f32_16x16x32_bf16 v[114:117], v[54:57], v[236:239], v[114:117]
	v_mfma_f32_16x16x32_bf16 v[110:113], v[70:73], v[236:239], v[110:113]
	v_mfma_f32_16x16x32_bf16 v[98:101], v[54:57], v[244:247], v[98:101]
	v_mfma_f32_16x16x32_bf16 v[94:97], v[70:73], v[244:247], v[94:97]
	v_mfma_f32_16x16x32_bf16 v[162:165], v[58:61], v[214:217], v[162:165]
	v_mfma_f32_16x16x32_bf16 v[142:145], v[74:77], v[214:217], v[142:145]
	v_mfma_f32_16x16x32_bf16 v[130:133], v[58:61], v[232:235], v[130:133]
	v_mfma_f32_16x16x32_bf16 v[126:129], v[74:77], v[232:235], v[126:129]
	v_mfma_f32_16x16x32_bf16 v[114:117], v[58:61], v[240:243], v[114:117]
	v_mfma_f32_16x16x32_bf16 v[110:113], v[74:77], v[240:243], v[110:113]
	v_mfma_f32_16x16x32_bf16 v[98:101], v[58:61], v[248:251], v[98:101]
	v_mfma_f32_16x16x32_bf16 v[94:97], v[74:77], v[248:251], v[94:97]
	v_mfma_f32_16x16x32_bf16 v[138:141], v[146:149], v[204:207], v[138:141]
	v_mfma_f32_16x16x32_bf16 v[134:137], v[154:157], v[204:207], v[134:137]
	v_mfma_f32_16x16x32_bf16 v[122:125], v[146:149], v[228:231], v[122:125]
	v_mfma_f32_16x16x32_bf16 v[118:121], v[154:157], v[228:231], v[118:121]
	v_mfma_f32_16x16x32_bf16 v[106:109], v[146:149], v[236:239], v[106:109]
	v_mfma_f32_16x16x32_bf16 v[102:105], v[154:157], v[236:239], v[102:105]
	v_mfma_f32_16x16x32_bf16 v[90:93], v[146:149], v[244:247], v[90:93]
	v_mfma_f32_16x16x32_bf16 v[86:89], v[154:157], v[244:247], v[86:89]
	v_mfma_f32_16x16x32_bf16 v[138:141], v[150:153], v[214:217], v[138:141]
	v_mfma_f32_16x16x32_bf16 v[134:137], v[158:161], v[214:217], v[134:137]
	v_mfma_f32_16x16x32_bf16 v[122:125], v[150:153], v[232:235], v[122:125]
	v_mfma_f32_16x16x32_bf16 v[118:121], v[158:161], v[232:235], v[118:121]
	v_mfma_f32_16x16x32_bf16 v[106:109], v[150:153], v[240:243], v[106:109]
	v_mfma_f32_16x16x32_bf16 v[102:105], v[158:161], v[240:243], v[102:105]
	v_mfma_f32_16x16x32_bf16 v[90:93], v[150:153], v[248:251], v[90:93]
	v_mfma_f32_16x16x32_bf16 v[86:89], v[158:161], v[248:251], v[86:89]
	s_setprio 0
	s_barrier
	s_add_i32 s6, s6, s43
	v_lshl_add_u64 v[226:227], v[218:219], 0, s[64:65]
	s_mov_b32 m0, s6
	ds_read_b128 v[204:207], v209 offset:49152
	ds_read_b128 v[214:217], v209 offset:50176
	ds_read_b128 v[228:231], v209 offset:51200
	ds_read_b128 v[232:235], v209 offset:52224
	ds_read_b128 v[236:239], v209 offset:53248
	ds_read_b128 v[240:243], v209 offset:54272
	ds_read_b128 v[244:247], v209 offset:55296
	ds_read_b128 v[248:251], v209 offset:56320
	global_load_lds_dwordx4 v[226:227], off
	v_lshl_add_u64 v[226:227], v[218:219], 0, s[62:63]
	s_add_i32 m0, s6, 0x2000
	s_add_i32 s6, s7, s43
	global_load_lds_dwordx4 v[226:227], off
	v_lshl_add_u64 v[226:227], v[218:219], 0, s[56:57]
	s_mov_b32 m0, s6
	v_lshl_add_u64 v[218:219], v[218:219], 0, s[58:59]
	global_load_lds_dwordx4 v[226:227], off
	s_add_i32 m0, s6, 0x2000
	s_nop 0
	global_load_lds_dwordx4 v[218:219], off
	v_lshl_add_u64 v[218:219], v[252:253], 0, s[66:67]
	s_mov_b32 m0, s22
	s_nop 0
	global_load_lds_dwordx4 v[218:219], off
	v_lshl_add_u64 v[218:219], v[252:253], 0, s[54:55]
	s_mov_b32 m0, s23
	s_nop 0
	global_load_lds_dwordx4 v[218:219], off
	s_waitcnt vmcnt(8)
	s_waitcnt lgkmcnt(0)
	s_barrier
	s_setprio 1
	v_mfma_f32_16x16x32_bf16 v[82:85], v[54:57], v[204:207], v[82:85]
	v_mfma_f32_16x16x32_bf16 v[78:81], v[70:73], v[204:207], v[78:81]
	v_mfma_f32_16x16x32_bf16 v[66:69], v[54:57], v[228:231], v[66:69]
	v_mfma_f32_16x16x32_bf16 v[62:65], v[70:73], v[228:231], v[62:65]
	v_mfma_f32_16x16x32_bf16 v[50:53], v[54:57], v[236:239], v[50:53]
	v_mfma_f32_16x16x32_bf16 v[46:49], v[70:73], v[236:239], v[46:49]
	v_mfma_f32_16x16x32_bf16 v[18:21], v[54:57], v[244:247], v[18:21]
	v_mfma_f32_16x16x32_bf16 v[14:17], v[70:73], v[244:247], v[14:17]
	v_mfma_f32_16x16x32_bf16 v[82:85], v[58:61], v[214:217], v[82:85]
	v_mfma_f32_16x16x32_bf16 v[78:81], v[74:77], v[214:217], v[78:81]
	v_mfma_f32_16x16x32_bf16 v[66:69], v[58:61], v[232:235], v[66:69]
	v_mfma_f32_16x16x32_bf16 v[62:65], v[74:77], v[232:235], v[62:65]
	v_mfma_f32_16x16x32_bf16 v[50:53], v[58:61], v[240:243], v[50:53]
	v_mfma_f32_16x16x32_bf16 v[46:49], v[74:77], v[240:243], v[46:49]
	v_mfma_f32_16x16x32_bf16 v[18:21], v[58:61], v[248:251], v[18:21]
	v_mfma_f32_16x16x32_bf16 v[14:17], v[74:77], v[248:251], v[14:17]
	v_mfma_f32_16x16x32_bf16 v[22:25], v[146:149], v[204:207], v[22:25]
	v_mfma_f32_16x16x32_bf16 v[74:77], v[150:153], v[214:217], v[22:25]
	v_mfma_f32_16x16x32_bf16 v[22:25], v[154:157], v[204:207], v[26:29]
	v_mfma_f32_16x16x32_bf16 v[70:73], v[158:161], v[214:217], v[22:25]
	v_mfma_f32_16x16x32_bf16 v[22:25], v[146:149], v[228:231], v[34:37]
	v_mfma_f32_16x16x32_bf16 v[58:61], v[150:153], v[232:235], v[22:25]
	v_mfma_f32_16x16x32_bf16 v[22:25], v[154:157], v[228:231], v[38:41]
	v_mfma_f32_16x16x32_bf16 v[54:57], v[158:161], v[232:235], v[22:25]
	v_mfma_f32_16x16x32_bf16 v[22:25], v[146:149], v[236:239], v[42:45]
	v_mfma_f32_16x16x32_bf16 v[42:45], v[150:153], v[240:243], v[22:25]
	v_mfma_f32_16x16x32_bf16 v[22:25], v[154:157], v[236:239], v[30:33]
	v_mfma_f32_16x16x32_bf16 v[10:13], v[146:149], v[244:247], v[10:13]
	v_mfma_f32_16x16x32_bf16 v[6:9], v[154:157], v[244:247], v[6:9]
	v_mfma_f32_16x16x32_bf16 v[30:33], v[158:161], v[240:243], v[22:25]
	v_mfma_f32_16x16x32_bf16 v[10:13], v[150:153], v[248:251], v[10:13]
	v_mfma_f32_16x16x32_bf16 v[6:9], v[158:161], v[248:251], v[6:9]
	s_setprio 0
	s_barrier
	s_add_i32 s38, s38, 2
	s_add_u32 s36, s36, 0x10000
	s_addc_u32 s37, s37, 0
	s_add_u32 s0, s0, 0x100
	s_addc_u32 s1, s1, 0
	s_cmp_gt_u32 s38, 13
	s_cbranch_scc0 .LBB0_222
	v_readlane_b32 s0, v255, 19
	v_readlane_b32 s1, v255, 20
	s_and_b64 vcc, exec, s[0:1]
	s_cbranch_vccz .LBB0_225
	s_barrier

.LBB0_1083:
	s_add_u32 s24, s22, 0xfffc0080
	s_addc_u32 s25, s23, -1
	s_add_i32 s46, 0, 0x10000
	s_cmp_eq_u32 s43, 12
	s_cselect_b32 s25, s13, s25
	s_cselect_b32 s24, s21, s24
	s_cselect_b32 s45, s11, s41
	s_cselect_b32 s44, s39, s40
	s_add_i32 s47, 0, 0x14000
	v_add_u32_e32 v130, s46, v194
	v_add_u32_e32 v158, s47, v194
	ds_read_b128 v[110:113], v130
	ds_read_b128 v[114:117], v130 offset:1024
	ds_read_b128 v[122:125], v130 offset:2048
	ds_read_b128 v[130:133], v130 offset:3072
	ds_read_b128 v[146:149], v158
	ds_read_b128 v[150:153], v158 offset:1024
	ds_read_b128 v[154:157], v158 offset:2048
	ds_read_b128 v[158:161], v158 offset:3072
	v_lshl_add_u64 v[218:219], s[22:23], 0, v[184:185]
	s_add_i32 m0, s26, 0xc000
	ds_read_b128 v[162:165], v196
	ds_read_b128 v[186:189], v196 offset:1024
	ds_read_b128 v[190:193], v196 offset:2048
	ds_read_b128 v[198:201], v196 offset:3072
	ds_read_b128 v[202:205], v196 offset:4096
	ds_read_b128 v[206:209], v196 offset:5120
	ds_read_b128 v[214:217], v196 offset:6144
	ds_read_b128 v[234:237], v196 offset:7168
	global_load_lds_dwordx4 v[218:219], off
	v_lshl_add_u64 v[218:219], v[218:219], 0, s[94:95]
	s_add_i32 m0, s26, 0xe000
	s_nop 0
	global_load_lds_dwordx4 v[218:219], off
	s_waitcnt vmcnt(8)
	s_waitcnt lgkmcnt(0)
	s_barrier
	s_setprio 1
	v_mfma_f32_16x16x32_bf16 v[142:145], v[110:113], v[162:165], v[142:145]
	v_mfma_f32_16x16x32_bf16 v[138:141], v[122:125], v[162:165], v[138:141]
	v_mfma_f32_16x16x32_bf16 v[118:121], v[110:113], v[190:193], v[118:121]
	v_mfma_f32_16x16x32_bf16 v[106:109], v[122:125], v[190:193], v[106:109]
	v_mfma_f32_16x16x32_bf16 v[94:97], v[110:113], v[202:205], v[94:97]
	v_mfma_f32_16x16x32_bf16 v[90:93], v[122:125], v[202:205], v[90:93]
	v_mfma_f32_16x16x32_bf16 v[78:81], v[110:113], v[214:217], v[78:81]
	v_mfma_f32_16x16x32_bf16 v[74:77], v[122:125], v[214:217], v[74:77]
	v_mfma_f32_16x16x32_bf16 v[142:145], v[114:117], v[186:189], v[142:145]
	v_mfma_f32_16x16x32_bf16 v[138:141], v[130:133], v[186:189], v[138:141]
	v_mfma_f32_16x16x32_bf16 v[118:121], v[114:117], v[198:201], v[118:121]
	v_mfma_f32_16x16x32_bf16 v[106:109], v[130:133], v[198:201], v[106:109]
	v_mfma_f32_16x16x32_bf16 v[94:97], v[114:117], v[206:209], v[94:97]
	v_mfma_f32_16x16x32_bf16 v[90:93], v[130:133], v[206:209], v[90:93]
	v_mfma_f32_16x16x32_bf16 v[78:81], v[114:117], v[234:237], v[78:81]
	v_mfma_f32_16x16x32_bf16 v[74:77], v[130:133], v[234:237], v[74:77]
	v_mfma_f32_16x16x32_bf16 v[134:137], v[146:149], v[162:165], v[134:137]
	v_mfma_f32_16x16x32_bf16 v[126:129], v[154:157], v[162:165], v[126:129]
	v_mfma_f32_16x16x32_bf16 v[102:105], v[146:149], v[190:193], v[102:105]
	v_mfma_f32_16x16x32_bf16 v[98:101], v[154:157], v[190:193], v[98:101]
	v_mfma_f32_16x16x32_bf16 v[86:89], v[146:149], v[202:205], v[86:89]
	v_mfma_f32_16x16x32_bf16 v[82:85], v[154:157], v[202:205], v[82:85]
	v_mfma_f32_16x16x32_bf16 v[70:73], v[146:149], v[214:217], v[70:73]
	v_mfma_f32_16x16x32_bf16 v[66:69], v[154:157], v[214:217], v[66:69]
	v_mfma_f32_16x16x32_bf16 v[134:137], v[150:153], v[186:189], v[134:137]
	v_mfma_f32_16x16x32_bf16 v[126:129], v[158:161], v[186:189], v[126:129]
	v_mfma_f32_16x16x32_bf16 v[102:105], v[150:153], v[198:201], v[102:105]
	v_mfma_f32_16x16x32_bf16 v[98:101], v[158:161], v[198:201], v[98:101]
	v_mfma_f32_16x16x32_bf16 v[86:89], v[150:153], v[206:209], v[86:89]
	v_mfma_f32_16x16x32_bf16 v[82:85], v[158:161], v[206:209], v[82:85]
	v_mfma_f32_16x16x32_bf16 v[70:73], v[150:153], v[234:237], v[70:73]
	v_mfma_f32_16x16x32_bf16 v[66:69], v[158:161], v[234:237], v[66:69]
	s_setprio 0
	s_barrier
	v_lshl_add_u64 v[218:219], s[44:45], 0, v[0:1]
	s_add_i32 s44, s46, s17
	s_mov_b32 m0, s44
	ds_read_b128 v[162:165], v196 offset:16384
	ds_read_b128 v[186:189], v196 offset:17408
	ds_read_b128 v[190:193], v196 offset:18432
	ds_read_b128 v[198:201], v196 offset:19456
	ds_read_b128 v[202:205], v196 offset:20480
	ds_read_b128 v[206:209], v196 offset:21504
	ds_read_b128 v[214:217], v196 offset:22528
	ds_read_b128 v[234:237], v196 offset:23552
	global_load_lds_dwordx4 v[218:219], off
	v_lshl_add_u64 v[238:239], v[218:219], 0, s[88:89]
	s_add_i32 m0, s44, 0x2000
	s_add_i32 s44, s47, s17
	global_load_lds_dwordx4 v[238:239], off
	v_lshl_add_u64 v[238:239], v[218:219], 0, s[90:91]
	s_mov_b32 m0, s44
	s_nop 0
	global_load_lds_dwordx4 v[238:239], off
	v_lshl_add_u64 v[238:239], v[218:219], 0, s[92:93]
	s_add_i32 m0, s44, 0x2000
	s_nop 0
	global_load_lds_dwordx4 v[238:239], off
	v_lshl_add_u64 v[238:239], s[24:25], 0, v[166:167]
	s_mov_b32 m0, s26
	v_lshl_add_u64 v[240:241], v[238:239], 0, s[94:95]
	global_load_lds_dwordx4 v[238:239], off
	s_mov_b32 m0, s27
	s_nop 0
	global_load_lds_dwordx4 v[240:241], off
	s_waitcnt vmcnt(8)
	s_waitcnt lgkmcnt(0)
	s_barrier
	s_setprio 1
	v_mfma_f32_16x16x32_bf16 v[62:65], v[110:113], v[162:165], v[62:65]
	v_mfma_f32_16x16x32_bf16 v[58:61], v[122:125], v[162:165], v[58:61]
	v_mfma_f32_16x16x32_bf16 v[46:49], v[110:113], v[190:193], v[46:49]
	v_mfma_f32_16x16x32_bf16 v[42:45], v[122:125], v[190:193], v[42:45]
	v_mfma_f32_16x16x32_bf16 v[30:33], v[110:113], v[202:205], v[30:33]
	v_mfma_f32_16x16x32_bf16 v[26:29], v[122:125], v[202:205], v[26:29]
	v_mfma_f32_16x16x32_bf16 v[14:17], v[110:113], v[214:217], v[14:17]
	v_mfma_f32_16x16x32_bf16 v[10:13], v[122:125], v[214:217], v[10:13]
	v_mfma_f32_16x16x32_bf16 v[62:65], v[114:117], v[186:189], v[62:65]
	v_mfma_f32_16x16x32_bf16 v[58:61], v[130:133], v[186:189], v[58:61]
	v_mfma_f32_16x16x32_bf16 v[46:49], v[114:117], v[198:201], v[46:49]
	v_mfma_f32_16x16x32_bf16 v[42:45], v[130:133], v[198:201], v[42:45]
	v_mfma_f32_16x16x32_bf16 v[30:33], v[114:117], v[206:209], v[30:33]
	v_mfma_f32_16x16x32_bf16 v[26:29], v[130:133], v[206:209], v[26:29]
	v_mfma_f32_16x16x32_bf16 v[14:17], v[114:117], v[234:237], v[14:17]
	v_mfma_f32_16x16x32_bf16 v[10:13], v[130:133], v[234:237], v[10:13]
	v_mfma_f32_16x16x32_bf16 v[54:57], v[146:149], v[162:165], v[54:57]
	v_mfma_f32_16x16x32_bf16 v[50:53], v[154:157], v[162:165], v[50:53]
	v_mfma_f32_16x16x32_bf16 v[38:41], v[146:149], v[190:193], v[38:41]
	v_mfma_f32_16x16x32_bf16 v[34:37], v[154:157], v[190:193], v[34:37]
	v_mfma_f32_16x16x32_bf16 v[22:25], v[146:149], v[202:205], v[22:25]
	v_mfma_f32_16x16x32_bf16 v[18:21], v[154:157], v[202:205], v[18:21]
	v_mfma_f32_16x16x32_bf16 v[6:9], v[146:149], v[214:217], v[6:9]
	v_mfma_f32_16x16x32_bf16 v[2:5], v[154:157], v[214:217], v[2:5]
	v_mfma_f32_16x16x32_bf16 v[54:57], v[150:153], v[186:189], v[54:57]
	v_mfma_f32_16x16x32_bf16 v[50:53], v[158:161], v[186:189], v[50:53]
	v_mfma_f32_16x16x32_bf16 v[38:41], v[150:153], v[198:201], v[38:41]
	v_mfma_f32_16x16x32_bf16 v[34:37], v[158:161], v[198:201], v[34:37]
	v_mfma_f32_16x16x32_bf16 v[22:25], v[150:153], v[206:209], v[22:25]
	v_mfma_f32_16x16x32_bf16 v[18:21], v[158:161], v[206:209], v[18:21]
	v_mfma_f32_16x16x32_bf16 v[6:9], v[150:153], v[234:237], v[6:9]
	v_mfma_f32_16x16x32_bf16 v[2:5], v[158:161], v[234:237], v[2:5]
	s_setprio 0
	s_barrier
	s_add_i32 s24, 0, 0x18000
	s_add_i32 s25, 0, 0x1c000
	v_add_u32_e32 v130, s24, v194
	v_add_u32_e32 v158, s25, v194
	ds_read_b128 v[110:113], v130
	ds_read_b128 v[114:117], v130 offset:1024
	ds_read_b128 v[122:125], v130 offset:2048
	ds_read_b128 v[130:133], v130 offset:3072
	ds_read_b128 v[146:149], v158
	ds_read_b128 v[150:153], v158 offset:1024
	ds_read_b128 v[154:157], v158 offset:2048
	ds_read_b128 v[158:161], v158 offset:3072
	s_mov_b32 m0, s28
	v_lshl_add_u64 v[240:241], v[238:239], 0, s[96:97]
	ds_read_b128 v[162:165], v196 offset:32768
	ds_read_b128 v[186:189], v196 offset:33792
	ds_read_b128 v[190:193], v196 offset:34816
	ds_read_b128 v[198:201], v196 offset:35840
	ds_read_b128 v[202:205], v196 offset:36864
	ds_read_b128 v[206:209], v196 offset:37888
	ds_read_b128 v[214:217], v196 offset:38912
	ds_read_b128 v[234:237], v196 offset:39936
	global_load_lds_dwordx4 v[240:241], off
	v_lshl_add_u64 v[240:241], v[238:239], 0, s[86:87]
	s_mov_b32 m0, s29
	s_nop 0
	global_load_lds_dwordx4 v[240:241], off
	s_waitcnt vmcnt(8)
	s_waitcnt lgkmcnt(0)
	s_barrier
	s_setprio 1
	v_mfma_f32_16x16x32_bf16 v[142:145], v[110:113], v[162:165], v[142:145]
	v_mfma_f32_16x16x32_bf16 v[138:141], v[122:125], v[162:165], v[138:141]
	v_mfma_f32_16x16x32_bf16 v[118:121], v[110:113], v[190:193], v[118:121]
	v_mfma_f32_16x16x32_bf16 v[106:109], v[122:125], v[190:193], v[106:109]
	v_mfma_f32_16x16x32_bf16 v[94:97], v[110:113], v[202:205], v[94:97]
	v_mfma_f32_16x16x32_bf16 v[90:93], v[122:125], v[202:205], v[90:93]
	v_mfma_f32_16x16x32_bf16 v[78:81], v[110:113], v[214:217], v[78:81]
	v_mfma_f32_16x16x32_bf16 v[74:77], v[122:125], v[214:217], v[74:77]
	v_mfma_f32_16x16x32_bf16 v[142:145], v[114:117], v[186:189], v[142:145]
	v_mfma_f32_16x16x32_bf16 v[138:141], v[130:133], v[186:189], v[138:141]
	v_mfma_f32_16x16x32_bf16 v[118:121], v[114:117], v[198:201], v[118:121]
	v_mfma_f32_16x16x32_bf16 v[106:109], v[130:133], v[198:201], v[106:109]
	v_mfma_f32_16x16x32_bf16 v[94:97], v[114:117], v[206:209], v[94:97]
	v_mfma_f32_16x16x32_bf16 v[90:93], v[130:133], v[206:209], v[90:93]
	v_mfma_f32_16x16x32_bf16 v[78:81], v[114:117], v[234:237], v[78:81]
	v_mfma_f32_16x16x32_bf16 v[74:77], v[130:133], v[234:237], v[74:77]
	v_mfma_f32_16x16x32_bf16 v[134:137], v[146:149], v[162:165], v[134:137]
	v_mfma_f32_16x16x32_bf16 v[126:129], v[154:157], v[162:165], v[126:129]
	v_mfma_f32_16x16x32_bf16 v[102:105], v[146:149], v[190:193], v[102:105]
	v_mfma_f32_16x16x32_bf16 v[98:101], v[154:157], v[190:193], v[98:101]
	v_mfma_f32_16x16x32_bf16 v[86:89], v[146:149], v[202:205], v[86:89]
	v_mfma_f32_16x16x32_bf16 v[82:85], v[154:157], v[202:205], v[82:85]
	v_mfma_f32_16x16x32_bf16 v[70:73], v[146:149], v[214:217], v[70:73]
	v_mfma_f32_16x16x32_bf16 v[66:69], v[154:157], v[214:217], v[66:69]
	v_mfma_f32_16x16x32_bf16 v[134:137], v[150:153], v[186:189], v[134:137]
	v_mfma_f32_16x16x32_bf16 v[126:129], v[158:161], v[186:189], v[126:129]
	v_mfma_f32_16x16x32_bf16 v[102:105], v[150:153], v[198:201], v[102:105]
	v_mfma_f32_16x16x32_bf16 v[98:101], v[158:161], v[198:201], v[98:101]
	v_mfma_f32_16x16x32_bf16 v[86:89], v[150:153], v[206:209], v[86:89]
	v_mfma_f32_16x16x32_bf16 v[82:85], v[158:161], v[206:209], v[82:85]
	v_mfma_f32_16x16x32_bf16 v[70:73], v[150:153], v[234:237], v[70:73]
	v_mfma_f32_16x16x32_bf16 v[66:69], v[158:161], v[234:237], v[66:69]
	s_setprio 0
	s_barrier
	s_add_i32 s24, s24, s17
	v_lshl_add_u64 v[240:241], v[218:219], 0, s[64:65]
	s_mov_b32 m0, s24
	ds_read_b128 v[162:165], v196 offset:49152
	ds_read_b128 v[186:189], v196 offset:50176
	ds_read_b128 v[190:193], v196 offset:51200
	ds_read_b128 v[198:201], v196 offset:52224
	ds_read_b128 v[202:205], v196 offset:53248
	ds_read_b128 v[206:209], v196 offset:54272
	ds_read_b128 v[214:217], v196 offset:55296
	ds_read_b128 v[234:237], v196 offset:56320
	global_load_lds_dwordx4 v[240:241], off
	v_lshl_add_u64 v[240:241], v[218:219], 0, s[62:63]
	s_add_i32 m0, s24, 0x2000
	s_add_i32 s24, s25, s17
	global_load_lds_dwordx4 v[240:241], off
	v_lshl_add_u64 v[240:241], v[218:219], 0, s[56:57]
	s_mov_b32 m0, s24
	v_lshl_add_u64 v[218:219], v[218:219], 0, s[58:59]
	global_load_lds_dwordx4 v[240:241], off
	s_add_i32 m0, s24, 0x2000
	s_nop 0
	global_load_lds_dwordx4 v[218:219], off
	v_lshl_add_u64 v[218:219], v[238:239], 0, s[66:67]
	s_mov_b32 m0, s35
	s_nop 0
	global_load_lds_dwordx4 v[218:219], off
	v_lshl_add_u64 v[218:219], v[238:239], 0, s[54:55]
	s_mov_b32 m0, s36
	s_nop 0
	global_load_lds_dwordx4 v[218:219], off
	s_waitcnt vmcnt(8)
	s_waitcnt lgkmcnt(0)
	s_barrier
	s_setprio 1
	v_mfma_f32_16x16x32_bf16 v[62:65], v[110:113], v[162:165], v[62:65]
	v_mfma_f32_16x16x32_bf16 v[58:61], v[122:125], v[162:165], v[58:61]
	v_mfma_f32_16x16x32_bf16 v[46:49], v[110:113], v[190:193], v[46:49]
	v_mfma_f32_16x16x32_bf16 v[42:45], v[122:125], v[190:193], v[42:45]
	v_mfma_f32_16x16x32_bf16 v[30:33], v[110:113], v[202:205], v[30:33]
	v_mfma_f32_16x16x32_bf16 v[26:29], v[122:125], v[202:205], v[26:29]
	v_mfma_f32_16x16x32_bf16 v[14:17], v[110:113], v[214:217], v[14:17]
	v_mfma_f32_16x16x32_bf16 v[10:13], v[122:125], v[214:217], v[10:13]
	v_mfma_f32_16x16x32_bf16 v[62:65], v[114:117], v[186:189], v[62:65]
	v_mfma_f32_16x16x32_bf16 v[58:61], v[130:133], v[186:189], v[58:61]
	v_mfma_f32_16x16x32_bf16 v[46:49], v[114:117], v[198:201], v[46:49]
	v_mfma_f32_16x16x32_bf16 v[42:45], v[130:133], v[198:201], v[42:45]
	v_mfma_f32_16x16x32_bf16 v[30:33], v[114:117], v[206:209], v[30:33]
	v_mfma_f32_16x16x32_bf16 v[26:29], v[130:133], v[206:209], v[26:29]
	v_mfma_f32_16x16x32_bf16 v[14:17], v[114:117], v[234:237], v[14:17]
	v_mfma_f32_16x16x32_bf16 v[10:13], v[130:133], v[234:237], v[10:13]
	v_mfma_f32_16x16x32_bf16 v[54:57], v[146:149], v[162:165], v[54:57]
	v_mfma_f32_16x16x32_bf16 v[50:53], v[154:157], v[162:165], v[50:53]
	v_mfma_f32_16x16x32_bf16 v[38:41], v[146:149], v[190:193], v[38:41]
	v_mfma_f32_16x16x32_bf16 v[34:37], v[154:157], v[190:193], v[34:37]
	v_mfma_f32_16x16x32_bf16 v[22:25], v[146:149], v[202:205], v[22:25]
	v_mfma_f32_16x16x32_bf16 v[18:21], v[154:157], v[202:205], v[18:21]
	v_mfma_f32_16x16x32_bf16 v[6:9], v[146:149], v[214:217], v[6:9]
	v_mfma_f32_16x16x32_bf16 v[2:5], v[154:157], v[214:217], v[2:5]
	v_mfma_f32_16x16x32_bf16 v[54:57], v[150:153], v[186:189], v[54:57]
	v_mfma_f32_16x16x32_bf16 v[50:53], v[158:161], v[186:189], v[50:53]
	v_mfma_f32_16x16x32_bf16 v[38:41], v[150:153], v[198:201], v[38:41]
	v_mfma_f32_16x16x32_bf16 v[34:37], v[158:161], v[198:201], v[34:37]
	v_mfma_f32_16x16x32_bf16 v[22:25], v[150:153], v[206:209], v[22:25]
	v_mfma_f32_16x16x32_bf16 v[18:21], v[158:161], v[206:209], v[18:21]
	v_mfma_f32_16x16x32_bf16 v[6:9], v[150:153], v[234:237], v[6:9]
	v_mfma_f32_16x16x32_bf16 v[2:5], v[158:161], v[234:237], v[2:5]
	s_setprio 0
	s_barrier
	s_add_i32 s43, s43, 2
	s_add_u32 s40, s40, 0x10000
	s_addc_u32 s41, s41, 0
	s_add_u32 s22, s22, 0x100
	s_addc_u32 s23, s23, 0
	s_cmp_gt_u32 s43, 13
	s_cbranch_scc0 .LBB0_1083
	s_and_b64 vcc, exec, s[8:9]
	s_movk_i32 s43, 0x1000
	s_cbranch_vccz .LBB0_1086
	s_barrier

.LBB0_1243:
	s_add_u32 s4, s14, 0xfffbe080
	s_addc_u32 s5, s15, -1
	s_add_i32 s2, 0, 0x10000
	s_cmp_eq_u32 s51, 12
	s_cselect_b32 s39, s31, s5
	s_cselect_b32 s38, s69, s4
	s_cselect_b32 s5, s29, s50
	s_cselect_b32 s4, vcc_lo, vcc_hi
	s_add_i32 s44, 0, 0x14000
	v_add_u32_e32 v144, s2, v193
	v_add_u32_e32 v182, s44, v193
	ds_read_b128 v[132:135], v144
	ds_read_b128 v[136:139], v144 offset:1024
	ds_read_b128 v[140:143], v144 offset:2048
	ds_read_b128 v[144:147], v144 offset:3072
	ds_read_b128 v[148:151], v182
	ds_read_b128 v[152:155], v182 offset:1024
	ds_read_b128 v[178:181], v182 offset:2048
	ds_read_b128 v[182:185], v182 offset:3072
	s_mov_b32 s40, 0xfffc0000
	v_lshl_add_u64 v[190:191], s[14:15], 0, v[176:177]
	s_mov_b32 s41, -1
	v_lshl_add_u64 v[208:209], v[190:191], 0, s[40:41]
	s_add_i32 m0, s25, 0xc000
	ds_read_b128 v[186:189], v199
	ds_read_b128 v[200:203], v199 offset:1024
	ds_read_b128 v[204:207], v199 offset:2048
	ds_read_b128 v[214:217], v199 offset:3072
	ds_read_b128 v[234:237], v199 offset:4096
	ds_read_b128 v[238:241], v199 offset:5120
	ds_read_b128 v[242:245], v199 offset:6144
	ds_read_b128 v[246:249], v199 offset:7168
	global_load_lds_dwordx4 v[208:209], off
	s_add_i32 m0, s25, 0xe000
	s_nop 0
	global_load_lds_dwordx4 v[190:191], off
	s_waitcnt vmcnt(8)
	s_waitcnt lgkmcnt(0)
	s_barrier
	s_setprio 1
	v_mfma_f32_16x16x32_bf16 v[64:67], v[132:135], v[186:189], v[64:67]
	v_mfma_f32_16x16x32_bf16 v[56:59], v[140:143], v[186:189], v[56:59]
	v_mfma_f32_16x16x32_bf16 v[60:63], v[132:135], v[204:207], v[60:63]
	v_mfma_f32_16x16x32_bf16 v[20:23], v[140:143], v[204:207], v[20:23]
	v_mfma_f32_16x16x32_bf16 v[128:131], v[132:135], v[234:237], v[128:131]
	v_mfma_f32_16x16x32_bf16 v[96:99], v[140:143], v[234:237], v[96:99]
	v_mfma_f32_16x16x32_bf16 v[124:127], v[132:135], v[242:245], v[124:127]
	v_mfma_f32_16x16x32_bf16 v[92:95], v[140:143], v[242:245], v[92:95]
	v_mfma_f32_16x16x32_bf16 v[64:67], v[136:139], v[200:203], v[64:67]
	v_mfma_f32_16x16x32_bf16 v[56:59], v[144:147], v[200:203], v[56:59]
	v_mfma_f32_16x16x32_bf16 v[60:63], v[136:139], v[214:217], v[60:63]
	v_mfma_f32_16x16x32_bf16 v[20:23], v[144:147], v[214:217], v[20:23]
	v_mfma_f32_16x16x32_bf16 v[128:131], v[136:139], v[238:241], v[128:131]
	v_mfma_f32_16x16x32_bf16 v[96:99], v[144:147], v[238:241], v[96:99]
	v_mfma_f32_16x16x32_bf16 v[124:127], v[136:139], v[246:249], v[124:127]
	v_mfma_f32_16x16x32_bf16 v[92:95], v[144:147], v[246:249], v[92:95]
	v_mfma_f32_16x16x32_bf16 v[48:51], v[148:151], v[186:189], v[48:51]
	v_mfma_f32_16x16x32_bf16 v[4:7], v[178:181], v[186:189], v[4:7]
	v_mfma_f32_16x16x32_bf16 v[44:47], v[148:151], v[204:207], v[44:47]
	v_mfma_f32_16x16x32_bf16 v[8:11], v[178:181], v[204:207], v[8:11]
	v_mfma_f32_16x16x32_bf16 v[120:123], v[148:151], v[234:237], v[120:123]
	v_mfma_f32_16x16x32_bf16 v[88:91], v[178:181], v[234:237], v[88:91]
	v_mfma_f32_16x16x32_bf16 v[112:115], v[148:151], v[242:245], v[112:115]
	v_mfma_f32_16x16x32_bf16 v[80:83], v[178:181], v[242:245], v[80:83]
	v_mfma_f32_16x16x32_bf16 v[48:51], v[152:155], v[200:203], v[48:51]
	v_mfma_f32_16x16x32_bf16 v[4:7], v[182:185], v[200:203], v[4:7]
	v_mfma_f32_16x16x32_bf16 v[44:47], v[152:155], v[214:217], v[44:47]
	v_mfma_f32_16x16x32_bf16 v[8:11], v[182:185], v[214:217], v[8:11]
	v_mfma_f32_16x16x32_bf16 v[120:123], v[152:155], v[238:241], v[120:123]
	v_mfma_f32_16x16x32_bf16 v[88:91], v[182:185], v[238:241], v[88:91]
	v_mfma_f32_16x16x32_bf16 v[112:115], v[152:155], v[246:249], v[112:115]
	v_mfma_f32_16x16x32_bf16 v[80:83], v[182:185], v[246:249], v[80:83]
	s_setprio 0
	s_barrier
	s_add_i32 s2, s2, s72
	v_lshl_add_u64 v[190:191], s[4:5], 0, v[0:1]
	s_mov_b32 m0, s2
	ds_read_b128 v[186:189], v199 offset:16384
	ds_read_b128 v[200:203], v199 offset:17408
	ds_read_b128 v[204:207], v199 offset:18432
	ds_read_b128 v[214:217], v199 offset:19456
	ds_read_b128 v[234:237], v199 offset:20480
	ds_read_b128 v[238:241], v199 offset:21504
	ds_read_b128 v[242:245], v199 offset:22528
	ds_read_b128 v[246:249], v199 offset:23552
	global_load_lds_dwordx4 v[190:191], off
	v_lshl_add_u64 v[208:209], v[190:191], 0, s[88:89]
	s_add_i32 m0, s2, 0x2000
	s_add_i32 s2, s44, s72
	global_load_lds_dwordx4 v[208:209], off
	v_lshl_add_u64 v[208:209], v[190:191], 0, s[90:91]
	s_mov_b32 m0, s2
	s_nop 0
	global_load_lds_dwordx4 v[208:209], off
	v_lshl_add_u64 v[208:209], v[190:191], 0, s[92:93]
	s_add_i32 m0, s2, 0x2000
	s_nop 0
	global_load_lds_dwordx4 v[208:209], off
	v_lshl_add_u64 v[208:209], s[38:39], 0, v[162:163]
	s_mov_b32 m0, s25
	v_lshl_add_u64 v[218:219], v[208:209], 0, s[96:97]
	global_load_lds_dwordx4 v[208:209], off
	s_mov_b32 m0, s78
	s_nop 0
	global_load_lds_dwordx4 v[218:219], off
	s_waitcnt vmcnt(8)
	s_waitcnt lgkmcnt(0)
	s_barrier
	s_setprio 1
	v_mfma_f32_16x16x32_bf16 v[116:119], v[132:135], v[186:189], v[116:119]
	v_mfma_f32_16x16x32_bf16 v[84:87], v[140:143], v[186:189], v[84:87]
	v_mfma_f32_16x16x32_bf16 v[108:111], v[132:135], v[204:207], v[108:111]
	v_mfma_f32_16x16x32_bf16 v[76:79], v[140:143], v[204:207], v[76:79]
	v_mfma_f32_16x16x32_bf16 v[52:55], v[132:135], v[234:237], v[52:55]
	v_mfma_f32_16x16x32_bf16 v[36:39], v[140:143], v[234:237], v[36:39]
	v_mfma_f32_16x16x32_bf16 v[40:43], v[132:135], v[242:245], v[40:43]
	v_mfma_f32_16x16x32_bf16 v[28:31], v[140:143], v[242:245], v[28:31]
	v_mfma_f32_16x16x32_bf16 v[116:119], v[136:139], v[200:203], v[116:119]
	v_mfma_f32_16x16x32_bf16 v[84:87], v[144:147], v[200:203], v[84:87]
	v_mfma_f32_16x16x32_bf16 v[108:111], v[136:139], v[214:217], v[108:111]
	v_mfma_f32_16x16x32_bf16 v[76:79], v[144:147], v[214:217], v[76:79]
	v_mfma_f32_16x16x32_bf16 v[52:55], v[136:139], v[238:241], v[52:55]
	v_mfma_f32_16x16x32_bf16 v[36:39], v[144:147], v[238:241], v[36:39]
	v_mfma_f32_16x16x32_bf16 v[40:43], v[136:139], v[246:249], v[40:43]
	v_mfma_f32_16x16x32_bf16 v[28:31], v[144:147], v[246:249], v[28:31]
	v_mfma_f32_16x16x32_bf16 v[104:107], v[148:151], v[186:189], v[104:107]
	v_mfma_f32_16x16x32_bf16 v[72:75], v[178:181], v[186:189], v[72:75]
	v_mfma_f32_16x16x32_bf16 v[100:103], v[148:151], v[204:207], v[100:103]
	v_mfma_f32_16x16x32_bf16 v[68:71], v[178:181], v[204:207], v[68:71]
	v_mfma_f32_16x16x32_bf16 v[32:35], v[148:151], v[234:237], v[32:35]
	v_mfma_f32_16x16x32_bf16 v[12:15], v[178:181], v[234:237], v[12:15]
	v_mfma_f32_16x16x32_bf16 v[24:27], v[148:151], v[242:245], v[24:27]
	v_mfma_f32_16x16x32_bf16 v[16:19], v[178:181], v[242:245], v[16:19]
	v_mfma_f32_16x16x32_bf16 v[104:107], v[152:155], v[200:203], v[104:107]
	v_mfma_f32_16x16x32_bf16 v[72:75], v[182:185], v[200:203], v[72:75]
	v_mfma_f32_16x16x32_bf16 v[100:103], v[152:155], v[214:217], v[100:103]
	v_mfma_f32_16x16x32_bf16 v[68:71], v[182:185], v[214:217], v[68:71]
	v_mfma_f32_16x16x32_bf16 v[32:35], v[152:155], v[238:241], v[32:35]
	v_mfma_f32_16x16x32_bf16 v[12:15], v[182:185], v[238:241], v[12:15]
	v_mfma_f32_16x16x32_bf16 v[24:27], v[152:155], v[246:249], v[24:27]
	v_mfma_f32_16x16x32_bf16 v[16:19], v[182:185], v[246:249], v[16:19]
	s_setprio 0
	s_barrier
	s_add_i32 s2, 0, 0x18000
	s_add_i32 s4, 0, 0x1c000
	v_add_u32_e32 v144, s2, v193
	v_add_u32_e32 v182, s4, v193
	ds_read_b128 v[132:135], v144
	ds_read_b128 v[136:139], v144 offset:1024
	ds_read_b128 v[140:143], v144 offset:2048
	ds_read_b128 v[144:147], v144 offset:3072
	ds_read_b128 v[148:151], v182
	ds_read_b128 v[152:155], v182 offset:1024
	ds_read_b128 v[178:181], v182 offset:2048
	ds_read_b128 v[182:185], v182 offset:3072
	s_mov_b32 m0, s79
	v_lshl_add_u64 v[218:219], v[208:209], 0, s[88:89]
	ds_read_b128 v[186:189], v199 offset:32768
	ds_read_b128 v[200:203], v199 offset:33792
	ds_read_b128 v[204:207], v199 offset:34816
	ds_read_b128 v[214:217], v199 offset:35840
	ds_read_b128 v[234:237], v199 offset:36864
	ds_read_b128 v[238:241], v199 offset:37888
	ds_read_b128 v[242:245], v199 offset:38912
	ds_read_b128 v[246:249], v199 offset:39936
	global_load_lds_dwordx4 v[218:219], off
	v_lshl_add_u64 v[218:219], v[208:209], 0, s[52:53]
	s_mov_b32 m0, s6
	s_nop 0
	global_load_lds_dwordx4 v[218:219], off
	s_waitcnt vmcnt(8)
	s_waitcnt lgkmcnt(0)
	s_barrier
	s_setprio 1
	v_mfma_f32_16x16x32_bf16 v[64:67], v[132:135], v[186:189], v[64:67]
	v_mfma_f32_16x16x32_bf16 v[56:59], v[140:143], v[186:189], v[56:59]
	v_mfma_f32_16x16x32_bf16 v[60:63], v[132:135], v[204:207], v[60:63]
	v_mfma_f32_16x16x32_bf16 v[20:23], v[140:143], v[204:207], v[20:23]
	v_mfma_f32_16x16x32_bf16 v[128:131], v[132:135], v[234:237], v[128:131]
	v_mfma_f32_16x16x32_bf16 v[96:99], v[140:143], v[234:237], v[96:99]
	v_mfma_f32_16x16x32_bf16 v[124:127], v[132:135], v[242:245], v[124:127]
	v_mfma_f32_16x16x32_bf16 v[92:95], v[140:143], v[242:245], v[92:95]
	v_mfma_f32_16x16x32_bf16 v[64:67], v[136:139], v[200:203], v[64:67]
	v_mfma_f32_16x16x32_bf16 v[56:59], v[144:147], v[200:203], v[56:59]
	v_mfma_f32_16x16x32_bf16 v[60:63], v[136:139], v[214:217], v[60:63]
	v_mfma_f32_16x16x32_bf16 v[20:23], v[144:147], v[214:217], v[20:23]
	v_mfma_f32_16x16x32_bf16 v[128:131], v[136:139], v[238:241], v[128:131]
	v_mfma_f32_16x16x32_bf16 v[96:99], v[144:147], v[238:241], v[96:99]
	v_mfma_f32_16x16x32_bf16 v[124:127], v[136:139], v[246:249], v[124:127]
	v_mfma_f32_16x16x32_bf16 v[92:95], v[144:147], v[246:249], v[92:95]
	v_mfma_f32_16x16x32_bf16 v[48:51], v[148:151], v[186:189], v[48:51]
	v_mfma_f32_16x16x32_bf16 v[4:7], v[178:181], v[186:189], v[4:7]
	v_mfma_f32_16x16x32_bf16 v[44:47], v[148:151], v[204:207], v[44:47]
	v_mfma_f32_16x16x32_bf16 v[8:11], v[178:181], v[204:207], v[8:11]
	v_mfma_f32_16x16x32_bf16 v[120:123], v[148:151], v[234:237], v[120:123]
	v_mfma_f32_16x16x32_bf16 v[88:91], v[178:181], v[234:237], v[88:91]
	v_mfma_f32_16x16x32_bf16 v[112:115], v[148:151], v[242:245], v[112:115]
	v_mfma_f32_16x16x32_bf16 v[80:83], v[178:181], v[242:245], v[80:83]
	v_mfma_f32_16x16x32_bf16 v[48:51], v[152:155], v[200:203], v[48:51]
	v_mfma_f32_16x16x32_bf16 v[4:7], v[182:185], v[200:203], v[4:7]
	v_mfma_f32_16x16x32_bf16 v[44:47], v[152:155], v[214:217], v[44:47]
	v_mfma_f32_16x16x32_bf16 v[8:11], v[182:185], v[214:217], v[8:11]
	v_mfma_f32_16x16x32_bf16 v[120:123], v[152:155], v[238:241], v[120:123]
	v_mfma_f32_16x16x32_bf16 v[88:91], v[182:185], v[238:241], v[88:91]
	v_mfma_f32_16x16x32_bf16 v[112:115], v[152:155], v[246:249], v[112:115]
	v_mfma_f32_16x16x32_bf16 v[80:83], v[182:185], v[246:249], v[80:83]
	s_setprio 0
	s_barrier
	s_add_i32 s2, s2, s72
	v_lshl_add_u64 v[218:219], v[190:191], 0, s[64:65]
	s_mov_b32 m0, s2
	ds_read_b128 v[186:189], v199 offset:49152
	ds_read_b128 v[200:203], v199 offset:50176
	ds_read_b128 v[204:207], v199 offset:51200
	ds_read_b128 v[214:217], v199 offset:52224
	ds_read_b128 v[234:237], v199 offset:53248
	ds_read_b128 v[238:241], v199 offset:54272
	ds_read_b128 v[242:245], v199 offset:55296
	ds_read_b128 v[246:249], v199 offset:56320
	global_load_lds_dwordx4 v[218:219], off
	v_lshl_add_u64 v[218:219], v[190:191], 0, s[62:63]
	s_add_i32 m0, s2, 0x2000
	s_add_i32 s2, s4, s72
	global_load_lds_dwordx4 v[218:219], off
	v_lshl_add_u64 v[218:219], v[190:191], 0, s[56:57]
	s_mov_b32 m0, s2
	v_lshl_add_u64 v[190:191], v[190:191], 0, s[58:59]
	global_load_lds_dwordx4 v[218:219], off
	s_add_i32 m0, s2, 0x2000
	s_nop 0
	global_load_lds_dwordx4 v[190:191], off
	v_lshl_add_u64 v[190:191], v[208:209], 0, s[66:67]
	s_mov_b32 m0, s7
	s_nop 0
	global_load_lds_dwordx4 v[190:191], off
	v_lshl_add_u64 v[190:191], v[208:209], 0, s[70:71]
	s_mov_b32 m0, s16
	s_nop 0
	global_load_lds_dwordx4 v[190:191], off
	s_waitcnt vmcnt(8)
	s_waitcnt lgkmcnt(0)
	s_barrier
	s_setprio 1
	v_mfma_f32_16x16x32_bf16 v[116:119], v[132:135], v[186:189], v[116:119]
	v_mfma_f32_16x16x32_bf16 v[84:87], v[140:143], v[186:189], v[84:87]
	v_mfma_f32_16x16x32_bf16 v[108:111], v[132:135], v[204:207], v[108:111]
	v_mfma_f32_16x16x32_bf16 v[76:79], v[140:143], v[204:207], v[76:79]
	v_mfma_f32_16x16x32_bf16 v[52:55], v[132:135], v[234:237], v[52:55]
	v_mfma_f32_16x16x32_bf16 v[36:39], v[140:143], v[234:237], v[36:39]
	v_mfma_f32_16x16x32_bf16 v[40:43], v[132:135], v[242:245], v[40:43]
	v_mfma_f32_16x16x32_bf16 v[28:31], v[140:143], v[242:245], v[28:31]
	v_mfma_f32_16x16x32_bf16 v[116:119], v[136:139], v[200:203], v[116:119]
	v_mfma_f32_16x16x32_bf16 v[84:87], v[144:147], v[200:203], v[84:87]
	v_mfma_f32_16x16x32_bf16 v[108:111], v[136:139], v[214:217], v[108:111]
	v_mfma_f32_16x16x32_bf16 v[76:79], v[144:147], v[214:217], v[76:79]
	v_mfma_f32_16x16x32_bf16 v[52:55], v[136:139], v[238:241], v[52:55]
	v_mfma_f32_16x16x32_bf16 v[36:39], v[144:147], v[238:241], v[36:39]
	v_mfma_f32_16x16x32_bf16 v[40:43], v[136:139], v[246:249], v[40:43]
	v_mfma_f32_16x16x32_bf16 v[28:31], v[144:147], v[246:249], v[28:31]
	v_mfma_f32_16x16x32_bf16 v[104:107], v[148:151], v[186:189], v[104:107]
	v_mfma_f32_16x16x32_bf16 v[72:75], v[178:181], v[186:189], v[72:75]
	v_mfma_f32_16x16x32_bf16 v[100:103], v[148:151], v[204:207], v[100:103]
	v_mfma_f32_16x16x32_bf16 v[68:71], v[178:181], v[204:207], v[68:71]
	v_mfma_f32_16x16x32_bf16 v[32:35], v[148:151], v[234:237], v[32:35]
	v_mfma_f32_16x16x32_bf16 v[12:15], v[178:181], v[234:237], v[12:15]
	v_mfma_f32_16x16x32_bf16 v[24:27], v[148:151], v[242:245], v[24:27]
	v_mfma_f32_16x16x32_bf16 v[16:19], v[178:181], v[242:245], v[16:19]
	v_mfma_f32_16x16x32_bf16 v[104:107], v[152:155], v[200:203], v[104:107]
	v_mfma_f32_16x16x32_bf16 v[72:75], v[182:185], v[200:203], v[72:75]
	v_mfma_f32_16x16x32_bf16 v[100:103], v[152:155], v[214:217], v[100:103]
	v_mfma_f32_16x16x32_bf16 v[68:71], v[182:185], v[214:217], v[68:71]
	v_mfma_f32_16x16x32_bf16 v[32:35], v[152:155], v[238:241], v[32:35]
	v_mfma_f32_16x16x32_bf16 v[12:15], v[182:185], v[238:241], v[12:15]
	v_mfma_f32_16x16x32_bf16 v[24:27], v[152:155], v[246:249], v[24:27]
	v_mfma_f32_16x16x32_bf16 v[16:19], v[182:185], v[246:249], v[16:19]
	s_setprio 0
	s_barrier
	s_add_i32 s51, s51, 2
	s_add_u32 vcc_hi, vcc_hi, 0x10000
	s_addc_u32 s50, s50, 0
	s_add_u32 s14, s14, 0x100
	s_addc_u32 s15, s15, 0
	s_cmp_gt_u32 s51, 13
	s_cbranch_scc0 .LBB0_1243
	v_lshl_or_b32 v178, s68, 7, v198
	v_mov_b32_e32 v179, 0
	v_lshlrev_b32_e32 v180, 2, v178
	v_mov_b32_e32 v181, 0
	v_lshl_add_u64 v[182:183], v[164:165], 0, v[180:181]
	global_load_dwordx4 v[132:135], v[182:183], off
	global_load_dwordx4 v[234:237], v[182:183], off offset:16
	v_lshl_add_u64 v[184:185], v[166:167], 0, v[180:181]
	global_load_dwordx4 v[136:139], v[184:185], off
	global_load_dwordx4 v[238:241], v[184:185], off offset:16
	v_lshl_add_u64 v[186:187], v[168:169], 0, v[180:181]
	global_load_dwordx4 v[140:143], v[186:187], off
	global_load_dwordx4 v[242:245], v[186:187], off offset:16
	v_lshl_add_u64 v[188:189], v[170:171], 0, v[180:181]
	global_load_dwordx4 v[144:147], v[188:189], off
	global_load_dwordx4 v[246:249], v[188:189], off offset:16
	v_lshl_add_u64 v[190:191], v[172:173], 0, v[180:181]
	global_load_dwordx4 v[148:151], v[190:191], off
	global_load_dwordx4 v[200:203], v[190:191], off offset:16
	v_lshl_add_u64 v[208:209], v[174:175], 0, v[180:181]
	global_load_dwordx4 v[152:155], v[208:209], off
	global_load_dwordx4 v[204:207], v[208:209], off offset:16
	s_and_b64 vcc, exec, s[26:27]
	s_cbranch_vccz .LBB0_1246
	s_barrier

.LBB0_1455:
	s_add_u32 s20, s14, 0xfff50080
	s_addc_u32 s21, s15, -1
	s_add_i32 s40, 0, 0x10000
	s_cmp_eq_u32 s37, 40
	s_cselect_b32 s21, s9, s21
	s_cselect_b32 s20, s8, s20
	s_cselect_b32 s39, s13, s36
	s_cselect_b32 s38, s12, s19
	s_add_i32 s41, 0, 0x14000
	v_add_u32_e32 v130, s40, v194
	v_add_u32_e32 v158, s41, v194
	ds_read_b128 v[110:113], v130
	ds_read_b128 v[114:117], v130 offset:1024
	ds_read_b128 v[122:125], v130 offset:2048
	ds_read_b128 v[130:133], v130 offset:3072
	ds_read_b128 v[146:149], v158
	ds_read_b128 v[150:153], v158 offset:1024
	ds_read_b128 v[154:157], v158 offset:2048
	ds_read_b128 v[158:161], v158 offset:3072
	v_lshl_add_u64 v[218:219], s[14:15], 0, v[184:185]
	s_add_i32 m0, s17, 0xc000
	ds_read_b128 v[162:165], v196
	ds_read_b128 v[186:189], v196 offset:1024
	ds_read_b128 v[190:193], v196 offset:2048
	ds_read_b128 v[198:201], v196 offset:3072
	ds_read_b128 v[202:205], v196 offset:4096
	ds_read_b128 v[206:209], v196 offset:5120
	ds_read_b128 v[214:217], v196 offset:6144
	ds_read_b128 v[234:237], v196 offset:7168
	global_load_lds_dwordx4 v[218:219], off
	v_lshl_add_u64 v[218:219], v[218:219], 0, s[76:77]
	s_add_i32 m0, s17, 0xe000
	s_nop 0
	global_load_lds_dwordx4 v[218:219], off
	s_waitcnt vmcnt(8)
	s_waitcnt lgkmcnt(0)
	s_barrier
	s_setprio 1
	v_mfma_f32_16x16x32_bf16 v[142:145], v[110:113], v[162:165], v[142:145]
	v_mfma_f32_16x16x32_bf16 v[138:141], v[122:125], v[162:165], v[138:141]
	v_mfma_f32_16x16x32_bf16 v[118:121], v[110:113], v[190:193], v[118:121]
	v_mfma_f32_16x16x32_bf16 v[106:109], v[122:125], v[190:193], v[106:109]
	v_mfma_f32_16x16x32_bf16 v[94:97], v[110:113], v[202:205], v[94:97]
	v_mfma_f32_16x16x32_bf16 v[90:93], v[122:125], v[202:205], v[90:93]
	v_mfma_f32_16x16x32_bf16 v[78:81], v[110:113], v[214:217], v[78:81]
	v_mfma_f32_16x16x32_bf16 v[74:77], v[122:125], v[214:217], v[74:77]
	v_mfma_f32_16x16x32_bf16 v[142:145], v[114:117], v[186:189], v[142:145]
	v_mfma_f32_16x16x32_bf16 v[138:141], v[130:133], v[186:189], v[138:141]
	v_mfma_f32_16x16x32_bf16 v[118:121], v[114:117], v[198:201], v[118:121]
	v_mfma_f32_16x16x32_bf16 v[106:109], v[130:133], v[198:201], v[106:109]
	v_mfma_f32_16x16x32_bf16 v[94:97], v[114:117], v[206:209], v[94:97]
	v_mfma_f32_16x16x32_bf16 v[90:93], v[130:133], v[206:209], v[90:93]
	v_mfma_f32_16x16x32_bf16 v[78:81], v[114:117], v[234:237], v[78:81]
	v_mfma_f32_16x16x32_bf16 v[74:77], v[130:133], v[234:237], v[74:77]
	v_mfma_f32_16x16x32_bf16 v[134:137], v[146:149], v[162:165], v[134:137]
	v_mfma_f32_16x16x32_bf16 v[126:129], v[154:157], v[162:165], v[126:129]
	v_mfma_f32_16x16x32_bf16 v[102:105], v[146:149], v[190:193], v[102:105]
	v_mfma_f32_16x16x32_bf16 v[98:101], v[154:157], v[190:193], v[98:101]
	v_mfma_f32_16x16x32_bf16 v[86:89], v[146:149], v[202:205], v[86:89]
	v_mfma_f32_16x16x32_bf16 v[82:85], v[154:157], v[202:205], v[82:85]
	v_mfma_f32_16x16x32_bf16 v[70:73], v[146:149], v[214:217], v[70:73]
	v_mfma_f32_16x16x32_bf16 v[66:69], v[154:157], v[214:217], v[66:69]
	v_mfma_f32_16x16x32_bf16 v[134:137], v[150:153], v[186:189], v[134:137]
	v_mfma_f32_16x16x32_bf16 v[126:129], v[158:161], v[186:189], v[126:129]
	v_mfma_f32_16x16x32_bf16 v[102:105], v[150:153], v[198:201], v[102:105]
	v_mfma_f32_16x16x32_bf16 v[98:101], v[158:161], v[198:201], v[98:101]
	v_mfma_f32_16x16x32_bf16 v[86:89], v[150:153], v[206:209], v[86:89]
	v_mfma_f32_16x16x32_bf16 v[82:85], v[158:161], v[206:209], v[82:85]
	v_mfma_f32_16x16x32_bf16 v[70:73], v[150:153], v[234:237], v[70:73]
	v_mfma_f32_16x16x32_bf16 v[66:69], v[158:161], v[234:237], v[66:69]
	s_setprio 0
	s_barrier
	v_lshl_add_u64 v[218:219], s[38:39], 0, v[0:1]
	s_add_i32 s38, s40, s16
	s_mov_b32 m0, s38
	ds_read_b128 v[162:165], v196 offset:16384
	ds_read_b128 v[186:189], v196 offset:17408
	ds_read_b128 v[190:193], v196 offset:18432
	ds_read_b128 v[198:201], v196 offset:19456
	ds_read_b128 v[202:205], v196 offset:20480
	ds_read_b128 v[206:209], v196 offset:21504
	ds_read_b128 v[214:217], v196 offset:22528
	ds_read_b128 v[234:237], v196 offset:23552
	global_load_lds_dwordx4 v[218:219], off
	v_lshl_add_u64 v[238:239], v[218:219], 0, s[88:89]
	s_add_i32 m0, s38, 0x2000
	s_add_i32 s38, s41, s16
	global_load_lds_dwordx4 v[238:239], off
	v_lshl_add_u64 v[238:239], v[218:219], 0, s[90:91]
	s_mov_b32 m0, s38
	s_nop 0
	global_load_lds_dwordx4 v[238:239], off
	v_lshl_add_u64 v[238:239], v[218:219], 0, s[92:93]
	s_add_i32 m0, s38, 0x2000
	s_nop 0
	global_load_lds_dwordx4 v[238:239], off
	v_lshl_add_u64 v[238:239], s[20:21], 0, v[166:167]
	s_mov_b32 m0, s17
	v_lshl_add_u64 v[240:241], v[238:239], 0, s[76:77]
	global_load_lds_dwordx4 v[238:239], off
	s_mov_b32 m0, s22
	s_nop 0
	global_load_lds_dwordx4 v[240:241], off
	s_waitcnt vmcnt(8)
	s_waitcnt lgkmcnt(0)
	s_barrier
	s_setprio 1
	v_mfma_f32_16x16x32_bf16 v[62:65], v[110:113], v[162:165], v[62:65]
	v_mfma_f32_16x16x32_bf16 v[58:61], v[122:125], v[162:165], v[58:61]
	v_mfma_f32_16x16x32_bf16 v[46:49], v[110:113], v[190:193], v[46:49]
	v_mfma_f32_16x16x32_bf16 v[42:45], v[122:125], v[190:193], v[42:45]
	v_mfma_f32_16x16x32_bf16 v[30:33], v[110:113], v[202:205], v[30:33]
	v_mfma_f32_16x16x32_bf16 v[26:29], v[122:125], v[202:205], v[26:29]
	v_mfma_f32_16x16x32_bf16 v[14:17], v[110:113], v[214:217], v[14:17]
	v_mfma_f32_16x16x32_bf16 v[10:13], v[122:125], v[214:217], v[10:13]
	v_mfma_f32_16x16x32_bf16 v[62:65], v[114:117], v[186:189], v[62:65]
	v_mfma_f32_16x16x32_bf16 v[58:61], v[130:133], v[186:189], v[58:61]
	v_mfma_f32_16x16x32_bf16 v[46:49], v[114:117], v[198:201], v[46:49]
	v_mfma_f32_16x16x32_bf16 v[42:45], v[130:133], v[198:201], v[42:45]
	v_mfma_f32_16x16x32_bf16 v[30:33], v[114:117], v[206:209], v[30:33]
	v_mfma_f32_16x16x32_bf16 v[26:29], v[130:133], v[206:209], v[26:29]
	v_mfma_f32_16x16x32_bf16 v[14:17], v[114:117], v[234:237], v[14:17]
	v_mfma_f32_16x16x32_bf16 v[10:13], v[130:133], v[234:237], v[10:13]
	v_mfma_f32_16x16x32_bf16 v[54:57], v[146:149], v[162:165], v[54:57]
	v_mfma_f32_16x16x32_bf16 v[50:53], v[154:157], v[162:165], v[50:53]
	v_mfma_f32_16x16x32_bf16 v[38:41], v[146:149], v[190:193], v[38:41]
	v_mfma_f32_16x16x32_bf16 v[34:37], v[154:157], v[190:193], v[34:37]
	v_mfma_f32_16x16x32_bf16 v[22:25], v[146:149], v[202:205], v[22:25]
	v_mfma_f32_16x16x32_bf16 v[18:21], v[154:157], v[202:205], v[18:21]
	v_mfma_f32_16x16x32_bf16 v[6:9], v[146:149], v[214:217], v[6:9]
	v_mfma_f32_16x16x32_bf16 v[2:5], v[154:157], v[214:217], v[2:5]
	v_mfma_f32_16x16x32_bf16 v[54:57], v[150:153], v[186:189], v[54:57]
	v_mfma_f32_16x16x32_bf16 v[50:53], v[158:161], v[186:189], v[50:53]
	v_mfma_f32_16x16x32_bf16 v[38:41], v[150:153], v[198:201], v[38:41]
	v_mfma_f32_16x16x32_bf16 v[34:37], v[158:161], v[198:201], v[34:37]
	v_mfma_f32_16x16x32_bf16 v[22:25], v[150:153], v[206:209], v[22:25]
	v_mfma_f32_16x16x32_bf16 v[18:21], v[158:161], v[206:209], v[18:21]
	v_mfma_f32_16x16x32_bf16 v[6:9], v[150:153], v[234:237], v[6:9]
	v_mfma_f32_16x16x32_bf16 v[2:5], v[158:161], v[234:237], v[2:5]
	s_setprio 0
	s_barrier
	s_add_i32 s20, 0, 0x18000
	s_add_i32 s21, 0, 0x1c000
	v_add_u32_e32 v130, s20, v194
	v_add_u32_e32 v158, s21, v194
	ds_read_b128 v[110:113], v130
	ds_read_b128 v[114:117], v130 offset:1024
	ds_read_b128 v[122:125], v130 offset:2048
	ds_read_b128 v[130:133], v130 offset:3072
	ds_read_b128 v[146:149], v158
	ds_read_b128 v[150:153], v158 offset:1024
	ds_read_b128 v[154:157], v158 offset:2048
	ds_read_b128 v[158:161], v158 offset:3072
	s_mov_b32 m0, s23
	v_lshl_add_u64 v[240:241], v[238:239], 0, s[60:61]
	ds_read_b128 v[162:165], v196 offset:32768
	ds_read_b128 v[186:189], v196 offset:33792
	ds_read_b128 v[190:193], v196 offset:34816
	ds_read_b128 v[198:201], v196 offset:35840
	ds_read_b128 v[202:205], v196 offset:36864
	ds_read_b128 v[206:209], v196 offset:37888
	ds_read_b128 v[214:217], v196 offset:38912
	ds_read_b128 v[234:237], v196 offset:39936
	global_load_lds_dwordx4 v[240:241], off
	v_lshl_add_u64 v[240:241], v[238:239], 0, s[82:83]
	s_mov_b32 m0, s24
	s_nop 0
	global_load_lds_dwordx4 v[240:241], off
	s_waitcnt vmcnt(8)
	s_waitcnt lgkmcnt(0)
	s_barrier
	s_setprio 1
	v_mfma_f32_16x16x32_bf16 v[142:145], v[110:113], v[162:165], v[142:145]
	v_mfma_f32_16x16x32_bf16 v[138:141], v[122:125], v[162:165], v[138:141]
	v_mfma_f32_16x16x32_bf16 v[118:121], v[110:113], v[190:193], v[118:121]
	v_mfma_f32_16x16x32_bf16 v[106:109], v[122:125], v[190:193], v[106:109]
	v_mfma_f32_16x16x32_bf16 v[94:97], v[110:113], v[202:205], v[94:97]
	v_mfma_f32_16x16x32_bf16 v[90:93], v[122:125], v[202:205], v[90:93]
	v_mfma_f32_16x16x32_bf16 v[78:81], v[110:113], v[214:217], v[78:81]
	v_mfma_f32_16x16x32_bf16 v[74:77], v[122:125], v[214:217], v[74:77]
	v_mfma_f32_16x16x32_bf16 v[142:145], v[114:117], v[186:189], v[142:145]
	v_mfma_f32_16x16x32_bf16 v[138:141], v[130:133], v[186:189], v[138:141]
	v_mfma_f32_16x16x32_bf16 v[118:121], v[114:117], v[198:201], v[118:121]
	v_mfma_f32_16x16x32_bf16 v[106:109], v[130:133], v[198:201], v[106:109]
	v_mfma_f32_16x16x32_bf16 v[94:97], v[114:117], v[206:209], v[94:97]
	v_mfma_f32_16x16x32_bf16 v[90:93], v[130:133], v[206:209], v[90:93]
	v_mfma_f32_16x16x32_bf16 v[78:81], v[114:117], v[234:237], v[78:81]
	v_mfma_f32_16x16x32_bf16 v[74:77], v[130:133], v[234:237], v[74:77]
	v_mfma_f32_16x16x32_bf16 v[134:137], v[146:149], v[162:165], v[134:137]
	v_mfma_f32_16x16x32_bf16 v[126:129], v[154:157], v[162:165], v[126:129]
	v_mfma_f32_16x16x32_bf16 v[102:105], v[146:149], v[190:193], v[102:105]
	v_mfma_f32_16x16x32_bf16 v[98:101], v[154:157], v[190:193], v[98:101]
	v_mfma_f32_16x16x32_bf16 v[86:89], v[146:149], v[202:205], v[86:89]
	v_mfma_f32_16x16x32_bf16 v[82:85], v[154:157], v[202:205], v[82:85]
	v_mfma_f32_16x16x32_bf16 v[70:73], v[146:149], v[214:217], v[70:73]
	v_mfma_f32_16x16x32_bf16 v[66:69], v[154:157], v[214:217], v[66:69]
	v_mfma_f32_16x16x32_bf16 v[134:137], v[150:153], v[186:189], v[134:137]
	v_mfma_f32_16x16x32_bf16 v[126:129], v[158:161], v[186:189], v[126:129]
	v_mfma_f32_16x16x32_bf16 v[102:105], v[150:153], v[198:201], v[102:105]
	v_mfma_f32_16x16x32_bf16 v[98:101], v[158:161], v[198:201], v[98:101]
	v_mfma_f32_16x16x32_bf16 v[86:89], v[150:153], v[206:209], v[86:89]
	v_mfma_f32_16x16x32_bf16 v[82:85], v[158:161], v[206:209], v[82:85]
	v_mfma_f32_16x16x32_bf16 v[70:73], v[150:153], v[234:237], v[70:73]
	v_mfma_f32_16x16x32_bf16 v[66:69], v[158:161], v[234:237], v[66:69]
	s_setprio 0
	s_barrier
	s_add_i32 s20, s20, s16
	v_lshl_add_u64 v[240:241], v[218:219], 0, s[64:65]
	s_mov_b32 m0, s20
	ds_read_b128 v[162:165], v196 offset:49152
	ds_read_b128 v[186:189], v196 offset:50176
	ds_read_b128 v[190:193], v196 offset:51200
	ds_read_b128 v[198:201], v196 offset:52224
	ds_read_b128 v[202:205], v196 offset:53248
	ds_read_b128 v[206:209], v196 offset:54272
	ds_read_b128 v[214:217], v196 offset:55296
	ds_read_b128 v[234:237], v196 offset:56320
	global_load_lds_dwordx4 v[240:241], off
	v_lshl_add_u64 v[240:241], v[218:219], 0, s[62:63]
	s_add_i32 m0, s20, 0x2000
	s_add_i32 s20, s21, s16
	global_load_lds_dwordx4 v[240:241], off
	v_lshl_add_u64 v[240:241], v[218:219], 0, s[56:57]
	s_mov_b32 m0, s20
	v_lshl_add_u64 v[218:219], v[218:219], 0, s[58:59]
	global_load_lds_dwordx4 v[240:241], off
	s_add_i32 m0, s20, 0x2000
	s_nop 0
	global_load_lds_dwordx4 v[218:219], off
	v_lshl_add_u64 v[218:219], v[238:239], 0, s[66:67]
	s_mov_b32 m0, s29
	s_nop 0
	global_load_lds_dwordx4 v[218:219], off
	v_lshl_add_u64 v[218:219], v[238:239], 0, s[84:85]
	s_mov_b32 m0, s30
	s_nop 0
	global_load_lds_dwordx4 v[218:219], off
	s_waitcnt vmcnt(8)
	s_waitcnt lgkmcnt(0)
	s_barrier
	s_setprio 1
	v_mfma_f32_16x16x32_bf16 v[62:65], v[110:113], v[162:165], v[62:65]
	v_mfma_f32_16x16x32_bf16 v[58:61], v[122:125], v[162:165], v[58:61]
	v_mfma_f32_16x16x32_bf16 v[46:49], v[110:113], v[190:193], v[46:49]
	v_mfma_f32_16x16x32_bf16 v[42:45], v[122:125], v[190:193], v[42:45]
	v_mfma_f32_16x16x32_bf16 v[30:33], v[110:113], v[202:205], v[30:33]
	v_mfma_f32_16x16x32_bf16 v[26:29], v[122:125], v[202:205], v[26:29]
	v_mfma_f32_16x16x32_bf16 v[14:17], v[110:113], v[214:217], v[14:17]
	v_mfma_f32_16x16x32_bf16 v[10:13], v[122:125], v[214:217], v[10:13]
	v_mfma_f32_16x16x32_bf16 v[62:65], v[114:117], v[186:189], v[62:65]
	v_mfma_f32_16x16x32_bf16 v[58:61], v[130:133], v[186:189], v[58:61]
	v_mfma_f32_16x16x32_bf16 v[46:49], v[114:117], v[198:201], v[46:49]
	v_mfma_f32_16x16x32_bf16 v[42:45], v[130:133], v[198:201], v[42:45]
	v_mfma_f32_16x16x32_bf16 v[30:33], v[114:117], v[206:209], v[30:33]
	v_mfma_f32_16x16x32_bf16 v[26:29], v[130:133], v[206:209], v[26:29]
	v_mfma_f32_16x16x32_bf16 v[14:17], v[114:117], v[234:237], v[14:17]
	v_mfma_f32_16x16x32_bf16 v[10:13], v[130:133], v[234:237], v[10:13]
	v_mfma_f32_16x16x32_bf16 v[54:57], v[146:149], v[162:165], v[54:57]
	v_mfma_f32_16x16x32_bf16 v[50:53], v[154:157], v[162:165], v[50:53]
	v_mfma_f32_16x16x32_bf16 v[38:41], v[146:149], v[190:193], v[38:41]
	v_mfma_f32_16x16x32_bf16 v[34:37], v[154:157], v[190:193], v[34:37]
	v_mfma_f32_16x16x32_bf16 v[22:25], v[146:149], v[202:205], v[22:25]
	v_mfma_f32_16x16x32_bf16 v[18:21], v[154:157], v[202:205], v[18:21]
	v_mfma_f32_16x16x32_bf16 v[6:9], v[146:149], v[214:217], v[6:9]
	v_mfma_f32_16x16x32_bf16 v[2:5], v[154:157], v[214:217], v[2:5]
	v_mfma_f32_16x16x32_bf16 v[54:57], v[150:153], v[186:189], v[54:57]
	v_mfma_f32_16x16x32_bf16 v[50:53], v[158:161], v[186:189], v[50:53]
	v_mfma_f32_16x16x32_bf16 v[38:41], v[150:153], v[198:201], v[38:41]
	v_mfma_f32_16x16x32_bf16 v[34:37], v[158:161], v[198:201], v[34:37]
	v_mfma_f32_16x16x32_bf16 v[22:25], v[150:153], v[206:209], v[22:25]
	v_mfma_f32_16x16x32_bf16 v[18:21], v[158:161], v[206:209], v[18:21]
	v_mfma_f32_16x16x32_bf16 v[6:9], v[150:153], v[234:237], v[6:9]
	v_mfma_f32_16x16x32_bf16 v[2:5], v[158:161], v[234:237], v[2:5]
	s_setprio 0
	s_barrier
	s_add_i32 s37, s37, 2
	s_add_u32 s19, s19, 0x10000
	s_addc_u32 s36, s36, 0
	s_add_u32 s14, s14, 0x100
	s_addc_u32 s15, s15, 0
	s_cmp_gt_u32 s37, 41
	s_cbranch_scc0 .LBB0_1455
	s_and_b64 vcc, exec, s[10:11]
	s_cbranch_vccz .LBB0_1458
	s_barrier

.LBB0_1497:
	v_readlane_b32 s50, v255, 13
	v_readlane_b32 s51, v255, 14
	s_and_b64 s[44:45], s[50:51], exec
	s_cbranch_scc0 .Lpn_H
	v_readlane_b32 s50, v255, 13
	v_readlane_b32 s51, v255, 14
	s_and_b64 s[44:45], s[50:51], exec
	s_cselect_b32 s1, 3, s78
	s_lshl_b32 s80, s1, 10
	s_lshl_b64 s[44:45], s[80:81], 2
	s_waitcnt vmcnt(28)
	v_lshlrev_b32_e32 v96, 16, v20
	v_and_b32_e32 v97, 0xffff0000, v20
	v_lshl_add_u64 v[18:19], v[18:19], 0, s[44:45]
	v_mov_b32_e32 v20, s17
	s_mul_i32 s80, s1, 0x4800
	v_cndmask_b32_e64 v18, v18, v20, s[50:51]
	v_mov_b32_e32 v20, s16
	s_lshl_b64 s[16:17], s[80:81], 2
	s_add_u32 s1, s8, s16
	s_addc_u32 s33, s9, s17
	s_add_u32 s8, s8, 0xe000000
	s_addc_u32 s9, s9, 0
	v_readlane_b32 s16, v254, 48
	s_cmp_gt_i32 s16, 31
	s_cselect_b32 s16, 0x6000, 0
	v_readlane_b32 s17, v254, 49
	s_add_u32 s16, s1, s16
	v_cndmask_b32_e64 v19, v19, v20, s[50:51]
	s_addc_u32 s17, s33, 0
	v_or_b32_e32 v20, 64, v30
	v_lshlrev_b32_e32 v104, 16, v24
	v_and_b32_e32 v106, 0xffff0000, v24
	s_add_u32 s44, s16, 0x1000
	v_mov_b32_e32 v27, v1
	v_lshlrev_b32_e32 v24, 4, v20
	v_or_b32_e32 v20, 0x80, v30
	v_lshlrev_b32_e32 v110, 16, v28
	v_and_b32_e32 v111, 0xffff0000, v28
	v_lshlrev_b32_e32 v112, 16, v29
	v_and_b32_e32 v113, 0xffff0000, v29
	v_and_b32_e32 v107, 0xffff0000, v25
	v_lshlrev_b32_e32 v100, 16, v22
	v_and_b32_e32 v101, 0xffff0000, v22
	s_addc_u32 s45, s17, 0
	v_lshl_add_u64 v[28:29], s[16:17], 0, v[26:27]
	v_lshlrev_b32_e32 v22, 4, v20
	v_or_b32_e32 v20, 0xc0, v30
	v_readlane_b32 s16, v255, 11
	v_lshlrev_b32_e32 v105, 16, v25
	v_lshlrev_b32_e32 v102, 16, v23
	v_and_b32_e32 v103, 0xffff0000, v23
	v_lshlrev_b32_e32 v98, 16, v21
	v_and_b32_e32 v99, 0xffff0000, v21
	v_mov_b32_e32 v25, v1
	v_mov_b32_e32 v23, v1
	v_lshlrev_b32_e32 v20, 4, v20
	v_mov_b32_e32 v21, v1
	v_readlane_b32 s17, v255, 12
	v_pk_mul_f32 v[114:115], v[106:107], v[106:107]
	v_mov_b32_e32 v108, v104
	v_mov_b32_e32 v109, v106
	v_lshl_add_u64 v[46:47], s[8:9], 0, v[0:1]
	v_lshl_add_u64 v[18:19], v[18:19], 0, v[26:27]
	v_lshl_add_u64 v[36:37], s[44:45], 0, v[26:27]
	v_lshl_add_u64 v[34:35], s[44:45], 0, v[24:25]
	v_lshl_add_u64 v[32:33], s[44:45], 0, v[22:23]
	v_lshl_add_u64 v[30:31], s[44:45], 0, v[20:21]
	s_mov_b64 s[50:51], -1
	s_and_b64 vcc, exec, s[16:17]
	v_mul_f32_e32 v25, v97, v97
	v_mul_f32_e32 v23, v98, v98
	v_mul_f32_e32 v21, v99, v99
	v_mul_f32_e32 v118, v113, v113
	v_pk_fma_f32 v[116:117], v[104:105], v[104:105], v[114:115]
	v_mul_f32_e32 v120, v111, v111
	v_mul_f32_e32 v114, v101, v101
	v_mul_f32_e32 v104, v103, v103
	s_cbranch_vccz .LBB0_1499
	v_pk_fma_f32 v[122:123], v[112:113], v[112:113], v[118:119] op_sel_hi:[1,1,0]
	v_pk_fma_f32 v[124:125], v[110:111], v[110:111], v[120:121] op_sel_hi:[1,1,0]
	v_mov_b32_e32 v127, v96
	v_mov_b32_e32 v126, v124
	v_mov_b32_e32 v128, v122
	v_mov_b32_e32 v129, v96
	v_pk_add_f32 v[122:123], v[124:125], v[122:123]
	v_pk_mul_f32 v[124:125], v[126:127], v[128:129]
	v_pk_fma_f32 v[126:127], v[102:103], v[102:103], v[104:105] op_sel_hi:[1,1,0]
	v_mov_b32_e32 v123, v125
	v_pk_add_f32 v[124:125], v[116:117], v[116:117] op_sel:[0,1] op_sel_hi:[1,0]
	v_mov_b32_e32 v127, v21
	v_mov_b32_e32 v125, v25
	v_pk_add_f32 v[122:123], v[122:123], v[124:125]
	v_pk_fma_f32 v[124:125], v[100:101], v[100:101], v[114:115] op_sel_hi:[1,1,0]
	s_mov_b32 s16, 0x800000
	v_mov_b32_e32 v125, v23
	v_pk_add_f32 v[124:125], v[124:125], v[126:127]
	global_load_dwordx4 v[126:129], v[18:19], off
	global_load_dwordx4 v[130:133], v[28:29], off
	global_load_dwordx4 v[134:137], v[36:37], off
	v_pk_add_f32 v[122:123], v[122:123], v[124:125]
	s_mov_b64 s[50:51], 0
	v_add_f32_e32 v27, v122, v123
	ds_bpermute_b32 v106, v227, v27
	v_lshl_add_u64 v[122:123], v[46:47], 0, s[46:47]
	s_waitcnt lgkmcnt(0)
	v_add_f32_e32 v27, v27, v106
	ds_bpermute_b32 v106, v228, v27
	s_waitcnt lgkmcnt(0)
	v_add_f32_e32 v27, v27, v106
	ds_bpermute_b32 v106, v229, v27
	s_waitcnt lgkmcnt(0)
	v_add_f32_e32 v27, v27, v106
	ds_bpermute_b32 v106, v230, v27
	s_waitcnt lgkmcnt(0)
	v_add_f32_e32 v27, v27, v106
	ds_bpermute_b32 v106, v231, v27
	s_waitcnt lgkmcnt(0)
	v_add_f32_e32 v27, v27, v106
	ds_bpermute_b32 v106, v232, v27
	s_waitcnt lgkmcnt(0)
	v_add_f32_e32 v27, v27, v106
	v_fmamk_f32 v27, v27, 0x3a800000, v222
	v_cmp_gt_f32_e32 vcc, s16, v27
	v_mul_f32_e32 v106, 0x4b800000, v27
	s_waitcnt vmcnt(0)
	v_pk_add_f32 v[134:135], v[134:135], 1.0 op_sel_hi:[1,0]
	v_cndmask_b32_e32 v27, v27, v106, vcc
	v_rsq_f32_e32 v27, v27
	v_pk_add_f32 v[136:137], v[136:137], 1.0 op_sel_hi:[1,0]
	v_mul_f32_e32 v106, 0x45800000, v27
	v_cndmask_b32_e32 v124, v27, v106, vcc
	v_pk_mul_f32 v[140:141], v[124:125], v[110:111] op_sel_hi:[0,1]
	v_pk_mul_f32 v[138:139], v[124:125], v[112:113] op_sel_hi:[0,1]
	v_pk_mul_f32 v[126:127], v[126:127], v[140:141]
	v_pk_mul_f32 v[128:129], v[128:129], v[138:139]
	v_pk_fma_f32 v[126:127], v[134:135], v[126:127], v[130:131]
	v_pk_fma_f32 v[128:129], v[136:137], v[128:129], v[132:133]
	v_cvt_pk_bf16_f32 v126, v126, v127
	v_mov_b32_e32 v106, v105
	v_cvt_pk_bf16_f32 v127, v128, v129
	global_store_dwordx2 v[122:123], v[126:127], off
	global_load_dwordx4 v[126:129], v[18:19], off offset:1024
	s_nop 0
	global_load_dwordx4 v[130:133], v[28:29], off offset:1024
	global_load_dwordx4 v[134:137], v[34:35], off
	v_pk_mul_f32 v[140:141], v[124:125], v[108:109] op_sel_hi:[0,1]
	v_pk_mul_f32 v[138:139], v[124:125], v[106:107] op_sel_hi:[0,1]
	s_waitcnt vmcnt(2)
	v_pk_mul_f32 v[126:127], v[126:127], v[140:141]
	v_pk_mul_f32 v[128:129], v[128:129], v[138:139]
	s_waitcnt vmcnt(0)
	v_pk_add_f32 v[134:135], v[134:135], 1.0 op_sel_hi:[1,0]
	v_pk_add_f32 v[136:137], v[136:137], 1.0 op_sel_hi:[1,0]
	v_pk_fma_f32 v[126:127], v[134:135], v[126:127], v[130:131]
	v_pk_fma_f32 v[128:129], v[136:137], v[128:129], v[132:133]
	v_cvt_pk_bf16_f32 v126, v126, v127
	v_pk_mul_f32 v[140:141], v[124:125], v[100:101] op_sel_hi:[0,1]
	v_cvt_pk_bf16_f32 v127, v128, v129
	global_store_dwordx2 v[122:123], v[126:127], off offset:512
	global_load_dwordx4 v[126:129], v[18:19], off offset:2048
	s_nop 0
	global_load_dwordx4 v[130:133], v[28:29], off offset:2048
	global_load_dwordx4 v[134:137], v[32:33], off
	v_pk_mul_f32 v[138:139], v[124:125], v[102:103] op_sel_hi:[0,1]
	s_waitcnt vmcnt(2)
	v_pk_mul_f32 v[126:127], v[140:141], v[126:127]
	v_pk_mul_f32 v[128:129], v[138:139], v[128:129]
	s_waitcnt vmcnt(0)
	v_pk_add_f32 v[134:135], v[134:135], 1.0 op_sel_hi:[1,0]
	v_pk_add_f32 v[136:137], v[136:137], 1.0 op_sel_hi:[1,0]
	v_pk_fma_f32 v[126:127], v[126:127], v[134:135], v[130:131]
	v_pk_fma_f32 v[128:129], v[128:129], v[136:137], v[132:133]
	v_cvt_pk_bf16_f32 v126, v126, v127
	v_pk_mul_f32 v[138:139], v[124:125], v[98:99] op_sel_hi:[0,1]
	v_cvt_pk_bf16_f32 v127, v128, v129
	global_store_dwordx2 v[122:123], v[126:127], off offset:1024
	global_load_dwordx4 v[126:129], v[18:19], off offset:3072
	s_nop 0
	global_load_dwordx4 v[130:133], v[28:29], off offset:3072
	global_load_dwordx4 v[134:137], v[30:31], off
	v_pk_mul_f32 v[124:125], v[124:125], v[96:97] op_sel_hi:[0,1]
	s_waitcnt vmcnt(2)
	v_pk_mul_f32 v[124:125], v[124:125], v[126:127]
	v_pk_mul_f32 v[126:127], v[138:139], v[128:129]
	s_waitcnt vmcnt(0)
	v_pk_add_f32 v[134:135], v[134:135], 1.0 op_sel_hi:[1,0]
	v_pk_add_f32 v[128:129], v[136:137], 1.0 op_sel_hi:[1,0]
	v_pk_fma_f32 v[124:125], v[124:125], v[134:135], v[130:131]
	v_pk_fma_f32 v[126:127], v[126:127], v[128:129], v[132:133]
	v_cvt_pk_bf16_f32 v124, v124, v125
	s_nop 0
	v_cvt_pk_bf16_f32 v125, v126, v127
	global_store_dwordx2 v[122:123], v[124:125], off offset:1536

.LBB0_1525:
	s_waitcnt vmcnt(2)
	s_nop 0
	v_and_b32_e32 v51, 0xffff0000, v43
	v_and_b32_e32 v50, 0xffff0000, v42
	v_lshlrev_b32_e32 v54, 16, v44
	v_and_b32_e32 v55, 0xffff0000, v44
	v_lshlrev_b32_e32 v56, 16, v45
	v_and_b32_e32 v57, 0xffff0000, v45
	v_lshlrev_b32_e32 v49, 16, v43
	v_lshlrev_b32_e32 v48, 16, v42
	s_waitcnt vmcnt(1)
	v_lshlrev_b32_e32 v42, 16, v40
	v_and_b32_e32 v43, 0xffff0000, v40
	v_lshlrev_b32_e32 v44, 16, v41
	v_and_b32_e32 v45, 0xffff0000, v41
	s_waitcnt vmcnt(0)
	v_lshlrev_b32_e32 v40, 16, v38
	v_and_b32_e32 v41, 0xffff0000, v38
	v_lshlrev_b32_e32 v38, 16, v39
	v_and_b32_e32 v39, 0xffff0000, v39
	v_pk_mul_f32 v[58:59], v[50:51], v[50:51]
	v_mov_b32_e32 v52, v48
	v_mov_b32_e32 v53, v50
	s_mov_b64 s[14:15], -1
	s_and_b64 vcc, exec, s[6:7]
	v_mul_f32_e32 v25, v41, v41
	v_mul_f32_e32 v23, v38, v38
	v_mul_f32_e32 v21, v39, v39
	v_mul_f32_e32 v62, v57, v57
	v_pk_fma_f32 v[60:61], v[48:49], v[48:49], v[58:59]
	v_mul_f32_e32 v64, v55, v55
	v_mul_f32_e32 v58, v43, v43
	v_mul_f32_e32 v48, v45, v45
	s_cbranch_vccz .LBB0_1543
	s_andn2_b64 vcc, exec, s[14:15]
	s_cbranch_vccz .LBB0_1544
	s_branch .LBB0_1527
.Lpn_H:
	s_waitcnt vmcnt(28)
	v_readfirstlane_b32 s28, v18
	v_readfirstlane_b32 s29, v19
	s_lshl_b32 s80, s78, 12
	s_mul_i32 s14, s78, 0x12000
	s_add_u32 s1, s8, s14
	s_addc_u32 s33, s9, 0
	v_readlane_b32 s16, v254, 48
	s_add_u32 s28, s28, s80
	s_addc_u32 s29, s29, 0
	s_add_u32 s8, s8, 0xe000000
	s_addc_u32 s9, s9, 0
	s_cmp_gt_i32 s16, 31
	s_cselect_b32 s16, 0x6000, 0
	s_add_u32 s20, s1, s16
	s_addc_u32 s21, s33, 0
	s_add_u32 s24, s20, 0x1000
	s_addc_u32 s25, s21, 0
	v_mov_b32_e32 v27, v1
	global_load_dwordx4 v[100:103], v26, s[28:29]
	global_load_dwordx4 v[116:119], v26, s[20:21]
	global_load_dwordx4 v[132:135], v26, s[24:25]
	global_load_dwordx4 v[104:107], v26, s[28:29] offset:1024
	global_load_dwordx4 v[120:123], v26, s[20:21] offset:1024
	global_load_dwordx4 v[136:139], v26, s[24:25] offset:1024
	global_load_dwordx4 v[108:111], v26, s[28:29] offset:2048
	global_load_dwordx4 v[124:127], v26, s[20:21] offset:2048
	global_load_dwordx4 v[140:143], v26, s[24:25] offset:2048
	global_load_dwordx4 v[112:115], v26, s[28:29] offset:3072
	global_load_dwordx4 v[128:131], v26, s[20:21] offset:3072
	global_load_dwordx4 v[144:147], v26, s[24:25] offset:3072
	v_lshl_add_u64 v[182:183], s[8:9], 0, v[0:1]
	s_waitcnt vmcnt(12)
	v_lshlrev_b32_e32 v166, 16, v28
	v_and_b32_e32 v167, 0xffff0000, v28
	v_lshlrev_b32_e32 v168, 16, v29
	v_and_b32_e32 v169, 0xffff0000, v29
	v_lshlrev_b32_e32 v170, 16, v24
	v_and_b32_e32 v171, 0xffff0000, v24
	v_lshlrev_b32_e32 v172, 16, v25
	v_and_b32_e32 v173, 0xffff0000, v25
	v_lshlrev_b32_e32 v174, 16, v22
	v_and_b32_e32 v175, 0xffff0000, v22
	v_lshlrev_b32_e32 v176, 16, v23
	v_and_b32_e32 v177, 0xffff0000, v23
	v_lshlrev_b32_e32 v178, 16, v20
	v_and_b32_e32 v179, 0xffff0000, v20
	v_lshlrev_b32_e32 v180, 16, v21
	v_and_b32_e32 v181, 0xffff0000, v21
	v_pk_mul_f32 v[186:187], v[166:167], v[166:167]
	v_pk_fma_f32 v[186:187], v[168:169], v[168:169], v[186:187]
	v_pk_fma_f32 v[186:187], v[170:171], v[170:171], v[186:187]
	v_pk_fma_f32 v[186:187], v[172:173], v[172:173], v[186:187]
	v_pk_fma_f32 v[186:187], v[174:175], v[174:175], v[186:187]
	v_pk_fma_f32 v[186:187], v[176:177], v[176:177], v[186:187]
	v_pk_fma_f32 v[186:187], v[178:179], v[178:179], v[186:187]
	v_pk_fma_f32 v[186:187], v[180:181], v[180:181], v[186:187]
	v_add_f32_e32 v150, v186, v187
	v_lshlrev_b32_e32 v166, 16, v94
	v_and_b32_e32 v167, 0xffff0000, v94
	v_lshlrev_b32_e32 v168, 16, v95
	v_and_b32_e32 v169, 0xffff0000, v95
	v_lshlrev_b32_e32 v170, 16, v92
	v_and_b32_e32 v171, 0xffff0000, v92
	v_lshlrev_b32_e32 v172, 16, v93
	v_and_b32_e32 v173, 0xffff0000, v93
	v_lshlrev_b32_e32 v174, 16, v90
	v_and_b32_e32 v175, 0xffff0000, v90
	v_lshlrev_b32_e32 v176, 16, v91
	v_and_b32_e32 v177, 0xffff0000, v91
	v_lshlrev_b32_e32 v178, 16, v88
	v_and_b32_e32 v179, 0xffff0000, v88
	v_lshlrev_b32_e32 v180, 16, v89
	v_and_b32_e32 v181, 0xffff0000, v89
	v_pk_mul_f32 v[186:187], v[166:167], v[166:167]
	v_pk_fma_f32 v[186:187], v[168:169], v[168:169], v[186:187]
	v_pk_fma_f32 v[186:187], v[170:171], v[170:171], v[186:187]
	v_pk_fma_f32 v[186:187], v[172:173], v[172:173], v[186:187]
	v_pk_fma_f32 v[186:187], v[174:175], v[174:175], v[186:187]
	v_pk_fma_f32 v[186:187], v[176:177], v[176:177], v[186:187]
	v_pk_fma_f32 v[186:187], v[178:179], v[178:179], v[186:187]
	v_pk_fma_f32 v[186:187], v[180:181], v[180:181], v[186:187]
	v_add_f32_e32 v152, v186, v187
	v_lshlrev_b32_e32 v166, 16, v86
	v_and_b32_e32 v167, 0xffff0000, v86
	v_lshlrev_b32_e32 v168, 16, v87
	v_and_b32_e32 v169, 0xffff0000, v87
	v_lshlrev_b32_e32 v170, 16, v84
	v_and_b32_e32 v171, 0xffff0000, v84
	v_lshlrev_b32_e32 v172, 16, v85
	v_and_b32_e32 v173, 0xffff0000, v85
	v_lshlrev_b32_e32 v174, 16, v82
	v_and_b32_e32 v175, 0xffff0000, v82
	v_lshlrev_b32_e32 v176, 16, v83
	v_and_b32_e32 v177, 0xffff0000, v83
	v_lshlrev_b32_e32 v178, 16, v80
	v_and_b32_e32 v179, 0xffff0000, v80
	v_lshlrev_b32_e32 v180, 16, v81
	v_and_b32_e32 v181, 0xffff0000, v81
	v_pk_mul_f32 v[186:187], v[166:167], v[166:167]
	v_pk_fma_f32 v[186:187], v[168:169], v[168:169], v[186:187]
	v_pk_fma_f32 v[186:187], v[170:171], v[170:171], v[186:187]
	v_pk_fma_f32 v[186:187], v[172:173], v[172:173], v[186:187]
	v_pk_fma_f32 v[186:187], v[174:175], v[174:175], v[186:187]
	v_pk_fma_f32 v[186:187], v[176:177], v[176:177], v[186:187]
	v_pk_fma_f32 v[186:187], v[178:179], v[178:179], v[186:187]
	v_pk_fma_f32 v[186:187], v[180:181], v[180:181], v[186:187]
	v_add_f32_e32 v154, v186, v187
	v_lshlrev_b32_e32 v166, 16, v78
	v_and_b32_e32 v167, 0xffff0000, v78
	v_lshlrev_b32_e32 v168, 16, v79
	v_and_b32_e32 v169, 0xffff0000, v79
	v_lshlrev_b32_e32 v170, 16, v76
	v_and_b32_e32 v171, 0xffff0000, v76
	v_lshlrev_b32_e32 v172, 16, v77
	v_and_b32_e32 v173, 0xffff0000, v77
	v_lshlrev_b32_e32 v174, 16, v74
	v_and_b32_e32 v175, 0xffff0000, v74
	v_lshlrev_b32_e32 v176, 16, v75
	v_and_b32_e32 v177, 0xffff0000, v75
	v_lshlrev_b32_e32 v178, 16, v72
	v_and_b32_e32 v179, 0xffff0000, v72
	v_lshlrev_b32_e32 v180, 16, v73
	v_and_b32_e32 v181, 0xffff0000, v73
	v_pk_mul_f32 v[186:187], v[166:167], v[166:167]
	v_pk_fma_f32 v[186:187], v[168:169], v[168:169], v[186:187]
	v_pk_fma_f32 v[186:187], v[170:171], v[170:171], v[186:187]
	v_pk_fma_f32 v[186:187], v[172:173], v[172:173], v[186:187]
	v_pk_fma_f32 v[186:187], v[174:175], v[174:175], v[186:187]
	v_pk_fma_f32 v[186:187], v[176:177], v[176:177], v[186:187]
	v_pk_fma_f32 v[186:187], v[178:179], v[178:179], v[186:187]
	v_pk_fma_f32 v[186:187], v[180:181], v[180:181], v[186:187]
	v_add_f32_e32 v156, v186, v187
	v_lshlrev_b32_e32 v166, 16, v70
	v_and_b32_e32 v167, 0xffff0000, v70
	v_lshlrev_b32_e32 v168, 16, v71
	v_and_b32_e32 v169, 0xffff0000, v71
	v_lshlrev_b32_e32 v170, 16, v68
	v_and_b32_e32 v171, 0xffff0000, v68
	v_lshlrev_b32_e32 v172, 16, v69
	v_and_b32_e32 v173, 0xffff0000, v69
	v_lshlrev_b32_e32 v174, 16, v66
	v_and_b32_e32 v175, 0xffff0000, v66
	v_lshlrev_b32_e32 v176, 16, v67
	v_and_b32_e32 v177, 0xffff0000, v67
	v_lshlrev_b32_e32 v178, 16, v64
	v_and_b32_e32 v179, 0xffff0000, v64
	v_lshlrev_b32_e32 v180, 16, v65
	v_and_b32_e32 v181, 0xffff0000, v65
	v_pk_mul_f32 v[186:187], v[166:167], v[166:167]
	v_pk_fma_f32 v[186:187], v[168:169], v[168:169], v[186:187]
	v_pk_fma_f32 v[186:187], v[170:171], v[170:171], v[186:187]
	v_pk_fma_f32 v[186:187], v[172:173], v[172:173], v[186:187]
	v_pk_fma_f32 v[186:187], v[174:175], v[174:175], v[186:187]
	v_pk_fma_f32 v[186:187], v[176:177], v[176:177], v[186:187]
	v_pk_fma_f32 v[186:187], v[178:179], v[178:179], v[186:187]
	v_pk_fma_f32 v[186:187], v[180:181], v[180:181], v[186:187]
	v_add_f32_e32 v158, v186, v187
	v_lshlrev_b32_e32 v166, 16, v62
	v_and_b32_e32 v167, 0xffff0000, v62
	v_lshlrev_b32_e32 v168, 16, v63
	v_and_b32_e32 v169, 0xffff0000, v63
	v_lshlrev_b32_e32 v170, 16, v60
	v_and_b32_e32 v171, 0xffff0000, v60
	v_lshlrev_b32_e32 v172, 16, v61
	v_and_b32_e32 v173, 0xffff0000, v61
	v_lshlrev_b32_e32 v174, 16, v58
	v_and_b32_e32 v175, 0xffff0000, v58
	v_lshlrev_b32_e32 v176, 16, v59
	v_and_b32_e32 v177, 0xffff0000, v59
	v_lshlrev_b32_e32 v178, 16, v56
	v_and_b32_e32 v179, 0xffff0000, v56
	v_lshlrev_b32_e32 v180, 16, v57
	v_and_b32_e32 v181, 0xffff0000, v57
	v_pk_mul_f32 v[186:187], v[166:167], v[166:167]
	v_pk_fma_f32 v[186:187], v[168:169], v[168:169], v[186:187]
	v_pk_fma_f32 v[186:187], v[170:171], v[170:171], v[186:187]
	v_pk_fma_f32 v[186:187], v[172:173], v[172:173], v[186:187]
	v_pk_fma_f32 v[186:187], v[174:175], v[174:175], v[186:187]
	v_pk_fma_f32 v[186:187], v[176:177], v[176:177], v[186:187]
	v_pk_fma_f32 v[186:187], v[178:179], v[178:179], v[186:187]
	v_pk_fma_f32 v[186:187], v[180:181], v[180:181], v[186:187]
	v_add_f32_e32 v160, v186, v187
	v_lshlrev_b32_e32 v166, 16, v54
	v_and_b32_e32 v167, 0xffff0000, v54
	v_lshlrev_b32_e32 v168, 16, v55
	v_and_b32_e32 v169, 0xffff0000, v55
	v_lshlrev_b32_e32 v170, 16, v52
	v_and_b32_e32 v171, 0xffff0000, v52
	v_lshlrev_b32_e32 v172, 16, v53
	v_and_b32_e32 v173, 0xffff0000, v53
	v_lshlrev_b32_e32 v174, 16, v50
	v_and_b32_e32 v175, 0xffff0000, v50
	v_lshlrev_b32_e32 v176, 16, v51
	v_and_b32_e32 v177, 0xffff0000, v51
	v_lshlrev_b32_e32 v178, 16, v48
	v_and_b32_e32 v179, 0xffff0000, v48
	v_lshlrev_b32_e32 v180, 16, v49
	v_and_b32_e32 v181, 0xffff0000, v49
	v_pk_mul_f32 v[186:187], v[166:167], v[166:167]
	v_pk_fma_f32 v[186:187], v[168:169], v[168:169], v[186:187]
	v_pk_fma_f32 v[186:187], v[170:171], v[170:171], v[186:187]
	v_pk_fma_f32 v[186:187], v[172:173], v[172:173], v[186:187]
	v_pk_fma_f32 v[186:187], v[174:175], v[174:175], v[186:187]
	v_pk_fma_f32 v[186:187], v[176:177], v[176:177], v[186:187]
	v_pk_fma_f32 v[186:187], v[178:179], v[178:179], v[186:187]
	v_pk_fma_f32 v[186:187], v[180:181], v[180:181], v[186:187]
	v_add_f32_e32 v162, v186, v187
	v_lshlrev_b32_e32 v166, 16, v44
	v_and_b32_e32 v167, 0xffff0000, v44
	v_lshlrev_b32_e32 v168, 16, v45
	v_and_b32_e32 v169, 0xffff0000, v45
	v_lshlrev_b32_e32 v170, 16, v42
	v_and_b32_e32 v171, 0xffff0000, v42
	v_lshlrev_b32_e32 v172, 16, v43
	v_and_b32_e32 v173, 0xffff0000, v43
	v_lshlrev_b32_e32 v174, 16, v40
	v_and_b32_e32 v175, 0xffff0000, v40
	v_lshlrev_b32_e32 v176, 16, v41
	v_and_b32_e32 v177, 0xffff0000, v41
	v_lshlrev_b32_e32 v178, 16, v38
	v_and_b32_e32 v179, 0xffff0000, v38
	v_lshlrev_b32_e32 v180, 16, v39
	v_and_b32_e32 v181, 0xffff0000, v39
	v_pk_mul_f32 v[186:187], v[166:167], v[166:167]
	v_pk_fma_f32 v[186:187], v[168:169], v[168:169], v[186:187]
	v_pk_fma_f32 v[186:187], v[170:171], v[170:171], v[186:187]
	v_pk_fma_f32 v[186:187], v[172:173], v[172:173], v[186:187]
	v_pk_fma_f32 v[186:187], v[174:175], v[174:175], v[186:187]
	v_pk_fma_f32 v[186:187], v[176:177], v[176:177], v[186:187]
	v_pk_fma_f32 v[186:187], v[178:179], v[178:179], v[186:187]
	v_pk_fma_f32 v[186:187], v[180:181], v[180:181], v[186:187]
	v_add_f32_e32 v164, v186, v187
	ds_bpermute_b32 v151, v227, v150
	ds_bpermute_b32 v153, v227, v152
	ds_bpermute_b32 v155, v227, v154
	ds_bpermute_b32 v157, v227, v156
	ds_bpermute_b32 v159, v227, v158
	ds_bpermute_b32 v161, v227, v160
	ds_bpermute_b32 v163, v227, v162
	ds_bpermute_b32 v165, v227, v164
	s_waitcnt lgkmcnt(0)
	v_add_f32_e32 v150, v150, v151
	v_add_f32_e32 v152, v152, v153
	v_add_f32_e32 v154, v154, v155
	v_add_f32_e32 v156, v156, v157
	v_add_f32_e32 v158, v158, v159
	v_add_f32_e32 v160, v160, v161
	v_add_f32_e32 v162, v162, v163
	v_add_f32_e32 v164, v164, v165
	ds_bpermute_b32 v151, v228, v150
	ds_bpermute_b32 v153, v228, v152
	ds_bpermute_b32 v155, v228, v154
	ds_bpermute_b32 v157, v228, v156
	ds_bpermute_b32 v159, v228, v158
	ds_bpermute_b32 v161, v228, v160
	ds_bpermute_b32 v163, v228, v162
	ds_bpermute_b32 v165, v228, v164
	s_waitcnt lgkmcnt(0)
	v_add_f32_e32 v150, v150, v151
	v_add_f32_e32 v152, v152, v153
	v_add_f32_e32 v154, v154, v155
	v_add_f32_e32 v156, v156, v157
	v_add_f32_e32 v158, v158, v159
	v_add_f32_e32 v160, v160, v161
	v_add_f32_e32 v162, v162, v163
	v_add_f32_e32 v164, v164, v165
	ds_bpermute_b32 v151, v229, v150
	ds_bpermute_b32 v153, v229, v152
	ds_bpermute_b32 v155, v229, v154
	ds_bpermute_b32 v157, v229, v156
	ds_bpermute_b32 v159, v229, v158
	ds_bpermute_b32 v161, v229, v160
	ds_bpermute_b32 v163, v229, v162
	ds_bpermute_b32 v165, v229, v164
	s_waitcnt lgkmcnt(0)
	v_add_f32_e32 v150, v150, v151
	v_add_f32_e32 v152, v152, v153
	v_add_f32_e32 v154, v154, v155
	v_add_f32_e32 v156, v156, v157
	v_add_f32_e32 v158, v158, v159
	v_add_f32_e32 v160, v160, v161
	v_add_f32_e32 v162, v162, v163
	v_add_f32_e32 v164, v164, v165
	ds_bpermute_b32 v151, v230, v150
	ds_bpermute_b32 v153, v230, v152
	ds_bpermute_b32 v155, v230, v154
	ds_bpermute_b32 v157, v230, v156
	ds_bpermute_b32 v159, v230, v158
	ds_bpermute_b32 v161, v230, v160
	ds_bpermute_b32 v163, v230, v162
	ds_bpermute_b32 v165, v230, v164
	s_waitcnt lgkmcnt(0)
	v_add_f32_e32 v150, v150, v151
	v_add_f32_e32 v152, v152, v153
	v_add_f32_e32 v154, v154, v155
	v_add_f32_e32 v156, v156, v157
	v_add_f32_e32 v158, v158, v159
	v_add_f32_e32 v160, v160, v161
	v_add_f32_e32 v162, v162, v163
	v_add_f32_e32 v164, v164, v165
	ds_bpermute_b32 v151, v231, v150
	ds_bpermute_b32 v153, v231, v152
	ds_bpermute_b32 v155, v231, v154
	ds_bpermute_b32 v157, v231, v156
	ds_bpermute_b32 v159, v231, v158
	ds_bpermute_b32 v161, v231, v160
	ds_bpermute_b32 v163, v231, v162
	ds_bpermute_b32 v165, v231, v164
	s_waitcnt lgkmcnt(0)
	v_add_f32_e32 v150, v150, v151
	v_add_f32_e32 v152, v152, v153
	v_add_f32_e32 v154, v154, v155
	v_add_f32_e32 v156, v156, v157
	v_add_f32_e32 v158, v158, v159
	v_add_f32_e32 v160, v160, v161
	v_add_f32_e32 v162, v162, v163
	v_add_f32_e32 v164, v164, v165
	ds_bpermute_b32 v151, v232, v150
	ds_bpermute_b32 v153, v232, v152
	ds_bpermute_b32 v155, v232, v154
	ds_bpermute_b32 v157, v232, v156
	ds_bpermute_b32 v159, v232, v158
	ds_bpermute_b32 v161, v232, v160
	ds_bpermute_b32 v163, v232, v162
	ds_bpermute_b32 v165, v232, v164
	s_waitcnt lgkmcnt(0)
	v_add_f32_e32 v150, v150, v151
	v_add_f32_e32 v152, v152, v153
	v_add_f32_e32 v154, v154, v155
	v_add_f32_e32 v156, v156, v157
	v_add_f32_e32 v158, v158, v159
	v_add_f32_e32 v160, v160, v161
	v_add_f32_e32 v162, v162, v163
	v_add_f32_e32 v164, v164, v165
	v_fmamk_f32 v150, v150, 0x3a800000, v222
	v_fmamk_f32 v152, v152, 0x3a800000, v222
	v_fmamk_f32 v154, v154, 0x3a800000, v222
	v_fmamk_f32 v156, v156, 0x3a800000, v222
	v_fmamk_f32 v158, v158, 0x3a800000, v222
	v_fmamk_f32 v160, v160, 0x3a800000, v222
	v_fmamk_f32 v162, v162, 0x3a800000, v222
	v_fmamk_f32 v164, v164, 0x3a800000, v222
	v_rsq_f32_e32 v150, v150
	v_rsq_f32_e32 v152, v152
	v_rsq_f32_e32 v154, v154
	v_rsq_f32_e32 v156, v156
	v_rsq_f32_e32 v158, v158
	v_rsq_f32_e32 v160, v160
	v_rsq_f32_e32 v162, v162
	v_rsq_f32_e32 v164, v164
	s_waitcnt vmcnt(0)
	v_pk_add_f32 v[132:133], v[132:133], 1.0 op_sel_hi:[1,0]
	v_pk_add_f32 v[134:135], v[134:135], 1.0 op_sel_hi:[1,0]
	v_pk_add_f32 v[136:137], v[136:137], 1.0 op_sel_hi:[1,0]
	v_pk_add_f32 v[138:139], v[138:139], 1.0 op_sel_hi:[1,0]
	v_pk_add_f32 v[140:141], v[140:141], 1.0 op_sel_hi:[1,0]
	v_pk_add_f32 v[142:143], v[142:143], 1.0 op_sel_hi:[1,0]
	v_pk_add_f32 v[144:145], v[144:145], 1.0 op_sel_hi:[1,0]
	v_pk_add_f32 v[146:147], v[146:147], 1.0 op_sel_hi:[1,0]
	v_lshlrev_b32_e32 v166, 16, v28
	v_and_b32_e32 v167, 0xffff0000, v28
	v_lshlrev_b32_e32 v168, 16, v29
	v_and_b32_e32 v169, 0xffff0000, v29
	v_lshlrev_b32_e32 v170, 16, v24
	v_and_b32_e32 v171, 0xffff0000, v24
	v_lshlrev_b32_e32 v172, 16, v25
	v_and_b32_e32 v173, 0xffff0000, v25
	v_lshlrev_b32_e32 v174, 16, v22
	v_and_b32_e32 v175, 0xffff0000, v22
	v_lshlrev_b32_e32 v176, 16, v23
	v_and_b32_e32 v177, 0xffff0000, v23
	v_lshlrev_b32_e32 v178, 16, v20
	v_and_b32_e32 v179, 0xffff0000, v20
	v_lshlrev_b32_e32 v180, 16, v21
	v_and_b32_e32 v181, 0xffff0000, v21
	v_lshl_add_u64 v[184:185], v[182:183], 0, s[46:47]
	v_pk_mul_f32 v[166:167], v[150:151], v[166:167] op_sel_hi:[0,1]
	v_pk_mul_f32 v[168:169], v[150:151], v[168:169] op_sel_hi:[0,1]
	v_pk_mul_f32 v[170:171], v[150:151], v[170:171] op_sel_hi:[0,1]
	v_pk_mul_f32 v[172:173], v[150:151], v[172:173] op_sel_hi:[0,1]
	v_pk_mul_f32 v[174:175], v[150:151], v[174:175] op_sel_hi:[0,1]
	v_pk_mul_f32 v[176:177], v[150:151], v[176:177] op_sel_hi:[0,1]
	v_pk_mul_f32 v[178:179], v[150:151], v[178:179] op_sel_hi:[0,1]
	v_pk_mul_f32 v[180:181], v[150:151], v[180:181] op_sel_hi:[0,1]
	v_pk_mul_f32 v[166:167], v[100:101], v[166:167]
	v_pk_mul_f32 v[168:169], v[102:103], v[168:169]
	v_pk_mul_f32 v[170:171], v[104:105], v[170:171]
	v_pk_mul_f32 v[172:173], v[106:107], v[172:173]
	v_pk_mul_f32 v[174:175], v[108:109], v[174:175]
	v_pk_mul_f32 v[176:177], v[110:111], v[176:177]
	v_pk_mul_f32 v[178:179], v[112:113], v[178:179]
	v_pk_mul_f32 v[180:181], v[114:115], v[180:181]
	v_pk_fma_f32 v[166:167], v[132:133], v[166:167], v[116:117]
	v_pk_fma_f32 v[168:169], v[134:135], v[168:169], v[118:119]
	v_pk_fma_f32 v[170:171], v[136:137], v[170:171], v[120:121]
	v_pk_fma_f32 v[172:173], v[138:139], v[172:173], v[122:123]
	v_pk_fma_f32 v[174:175], v[140:141], v[174:175], v[124:125]
	v_pk_fma_f32 v[176:177], v[142:143], v[176:177], v[126:127]
	v_pk_fma_f32 v[178:179], v[144:145], v[178:179], v[128:129]
	v_pk_fma_f32 v[180:181], v[146:147], v[180:181], v[130:131]
	v_cvt_pk_bf16_f32 v166, v166, v167
	v_cvt_pk_bf16_f32 v167, v168, v169
	v_cvt_pk_bf16_f32 v170, v170, v171
	v_cvt_pk_bf16_f32 v171, v172, v173
	v_cvt_pk_bf16_f32 v174, v174, v175
	v_cvt_pk_bf16_f32 v175, v176, v177
	v_cvt_pk_bf16_f32 v178, v178, v179
	v_cvt_pk_bf16_f32 v179, v180, v181
	global_store_dwordx2 v[184:185], v[166:167], off
	global_store_dwordx2 v[184:185], v[170:171], off offset:512
	global_store_dwordx2 v[184:185], v[174:175], off offset:1024
	global_store_dwordx2 v[184:185], v[178:179], off offset:1536
	v_lshlrev_b32_e32 v166, 16, v94
	v_and_b32_e32 v167, 0xffff0000, v94
	v_lshlrev_b32_e32 v168, 16, v95
	v_and_b32_e32 v169, 0xffff0000, v95
	v_lshlrev_b32_e32 v170, 16, v92
	v_and_b32_e32 v171, 0xffff0000, v92
	v_lshlrev_b32_e32 v172, 16, v93
	v_and_b32_e32 v173, 0xffff0000, v93
	v_lshlrev_b32_e32 v174, 16, v90
	v_and_b32_e32 v175, 0xffff0000, v90
	v_lshlrev_b32_e32 v176, 16, v91
	v_and_b32_e32 v177, 0xffff0000, v91
	v_lshlrev_b32_e32 v178, 16, v88
	v_and_b32_e32 v179, 0xffff0000, v88
	v_lshlrev_b32_e32 v180, 16, v89
	v_and_b32_e32 v181, 0xffff0000, v89
	v_lshl_add_u64 v[184:185], v[182:183], 0, s[40:41]
	v_pk_mul_f32 v[166:167], v[152:153], v[166:167] op_sel_hi:[0,1]
	v_pk_mul_f32 v[168:169], v[152:153], v[168:169] op_sel_hi:[0,1]
	v_pk_mul_f32 v[170:171], v[152:153], v[170:171] op_sel_hi:[0,1]
	v_pk_mul_f32 v[172:173], v[152:153], v[172:173] op_sel_hi:[0,1]
	v_pk_mul_f32 v[174:175], v[152:153], v[174:175] op_sel_hi:[0,1]
	v_pk_mul_f32 v[176:177], v[152:153], v[176:177] op_sel_hi:[0,1]
	v_pk_mul_f32 v[178:179], v[152:153], v[178:179] op_sel_hi:[0,1]
	v_pk_mul_f32 v[180:181], v[152:153], v[180:181] op_sel_hi:[0,1]
	v_pk_mul_f32 v[166:167], v[100:101], v[166:167]
	v_pk_mul_f32 v[168:169], v[102:103], v[168:169]
	v_pk_mul_f32 v[170:171], v[104:105], v[170:171]
	v_pk_mul_f32 v[172:173], v[106:107], v[172:173]
	v_pk_mul_f32 v[174:175], v[108:109], v[174:175]
	v_pk_mul_f32 v[176:177], v[110:111], v[176:177]
	v_pk_mul_f32 v[178:179], v[112:113], v[178:179]
	v_pk_mul_f32 v[180:181], v[114:115], v[180:181]
	v_pk_fma_f32 v[166:167], v[132:133], v[166:167], v[116:117]
	v_pk_fma_f32 v[168:169], v[134:135], v[168:169], v[118:119]
	v_pk_fma_f32 v[170:171], v[136:137], v[170:171], v[120:121]
	v_pk_fma_f32 v[172:173], v[138:139], v[172:173], v[122:123]
	v_pk_fma_f32 v[174:175], v[140:141], v[174:175], v[124:125]
	v_pk_fma_f32 v[176:177], v[142:143], v[176:177], v[126:127]
	v_pk_fma_f32 v[178:179], v[144:145], v[178:179], v[128:129]
	v_pk_fma_f32 v[180:181], v[146:147], v[180:181], v[130:131]
	v_cvt_pk_bf16_f32 v166, v166, v167
	v_cvt_pk_bf16_f32 v167, v168, v169
	v_cvt_pk_bf16_f32 v170, v170, v171
	v_cvt_pk_bf16_f32 v171, v172, v173
	v_cvt_pk_bf16_f32 v174, v174, v175
	v_cvt_pk_bf16_f32 v175, v176, v177
	v_cvt_pk_bf16_f32 v178, v178, v179
	v_cvt_pk_bf16_f32 v179, v180, v181
	global_store_dwordx2 v[184:185], v[166:167], off
	global_store_dwordx2 v[184:185], v[170:171], off offset:512
	global_store_dwordx2 v[184:185], v[174:175], off offset:1024
	global_store_dwordx2 v[184:185], v[178:179], off offset:1536
	v_lshlrev_b32_e32 v166, 16, v86
	v_and_b32_e32 v167, 0xffff0000, v86
	v_lshlrev_b32_e32 v168, 16, v87
	v_and_b32_e32 v169, 0xffff0000, v87
	v_lshlrev_b32_e32 v170, 16, v84
	v_and_b32_e32 v171, 0xffff0000, v84
	v_lshlrev_b32_e32 v172, 16, v85
	v_and_b32_e32 v173, 0xffff0000, v85
	v_lshlrev_b32_e32 v174, 16, v82
	v_and_b32_e32 v175, 0xffff0000, v82
	v_lshlrev_b32_e32 v176, 16, v83
	v_and_b32_e32 v177, 0xffff0000, v83
	v_lshlrev_b32_e32 v178, 16, v80
	v_and_b32_e32 v179, 0xffff0000, v80
	v_lshlrev_b32_e32 v180, 16, v81
	v_and_b32_e32 v181, 0xffff0000, v81
	v_lshl_add_u64 v[184:185], v[182:183], 0, s[36:37]
	v_pk_mul_f32 v[166:167], v[154:155], v[166:167] op_sel_hi:[0,1]
	v_pk_mul_f32 v[168:169], v[154:155], v[168:169] op_sel_hi:[0,1]
	v_pk_mul_f32 v[170:171], v[154:155], v[170:171] op_sel_hi:[0,1]
	v_pk_mul_f32 v[172:173], v[154:155], v[172:173] op_sel_hi:[0,1]
	v_pk_mul_f32 v[174:175], v[154:155], v[174:175] op_sel_hi:[0,1]
	v_pk_mul_f32 v[176:177], v[154:155], v[176:177] op_sel_hi:[0,1]
	v_pk_mul_f32 v[178:179], v[154:155], v[178:179] op_sel_hi:[0,1]
	v_pk_mul_f32 v[180:181], v[154:155], v[180:181] op_sel_hi:[0,1]
	v_pk_mul_f32 v[166:167], v[100:101], v[166:167]
	v_pk_mul_f32 v[168:169], v[102:103], v[168:169]
	v_pk_mul_f32 v[170:171], v[104:105], v[170:171]
	v_pk_mul_f32 v[172:173], v[106:107], v[172:173]
	v_pk_mul_f32 v[174:175], v[108:109], v[174:175]
	v_pk_mul_f32 v[176:177], v[110:111], v[176:177]
	v_pk_mul_f32 v[178:179], v[112:113], v[178:179]
	v_pk_mul_f32 v[180:181], v[114:115], v[180:181]
	v_pk_fma_f32 v[166:167], v[132:133], v[166:167], v[116:117]
	v_pk_fma_f32 v[168:169], v[134:135], v[168:169], v[118:119]
	v_pk_fma_f32 v[170:171], v[136:137], v[170:171], v[120:121]
	v_pk_fma_f32 v[172:173], v[138:139], v[172:173], v[122:123]
	v_pk_fma_f32 v[174:175], v[140:141], v[174:175], v[124:125]
	v_pk_fma_f32 v[176:177], v[142:143], v[176:177], v[126:127]
	v_pk_fma_f32 v[178:179], v[144:145], v[178:179], v[128:129]
	v_pk_fma_f32 v[180:181], v[146:147], v[180:181], v[130:131]
	v_cvt_pk_bf16_f32 v166, v166, v167
	v_cvt_pk_bf16_f32 v167, v168, v169
	v_cvt_pk_bf16_f32 v170, v170, v171
	v_cvt_pk_bf16_f32 v171, v172, v173
	v_cvt_pk_bf16_f32 v174, v174, v175
	v_cvt_pk_bf16_f32 v175, v176, v177
	v_cvt_pk_bf16_f32 v178, v178, v179
	v_cvt_pk_bf16_f32 v179, v180, v181
	global_store_dwordx2 v[184:185], v[166:167], off
	global_store_dwordx2 v[184:185], v[170:171], off offset:512
	global_store_dwordx2 v[184:185], v[174:175], off offset:1024
	global_store_dwordx2 v[184:185], v[178:179], off offset:1536
	v_lshlrev_b32_e32 v166, 16, v78
	v_and_b32_e32 v167, 0xffff0000, v78
	v_lshlrev_b32_e32 v168, 16, v79
	v_and_b32_e32 v169, 0xffff0000, v79
	v_lshlrev_b32_e32 v170, 16, v76
	v_and_b32_e32 v171, 0xffff0000, v76
	v_lshlrev_b32_e32 v172, 16, v77
	v_and_b32_e32 v173, 0xffff0000, v77
	v_lshlrev_b32_e32 v174, 16, v74
	v_and_b32_e32 v175, 0xffff0000, v74
	v_lshlrev_b32_e32 v176, 16, v75
	v_and_b32_e32 v177, 0xffff0000, v75
	v_lshlrev_b32_e32 v178, 16, v72
	v_and_b32_e32 v179, 0xffff0000, v72
	v_lshlrev_b32_e32 v180, 16, v73
	v_and_b32_e32 v181, 0xffff0000, v73
	v_lshl_add_u64 v[184:185], v[182:183], 0, s[30:31]
	v_pk_mul_f32 v[166:167], v[156:157], v[166:167] op_sel_hi:[0,1]
	v_pk_mul_f32 v[168:169], v[156:157], v[168:169] op_sel_hi:[0,1]
	v_pk_mul_f32 v[170:171], v[156:157], v[170:171] op_sel_hi:[0,1]
	v_pk_mul_f32 v[172:173], v[156:157], v[172:173] op_sel_hi:[0,1]
	v_pk_mul_f32 v[174:175], v[156:157], v[174:175] op_sel_hi:[0,1]
	v_pk_mul_f32 v[176:177], v[156:157], v[176:177] op_sel_hi:[0,1]
	v_pk_mul_f32 v[178:179], v[156:157], v[178:179] op_sel_hi:[0,1]
	v_pk_mul_f32 v[180:181], v[156:157], v[180:181] op_sel_hi:[0,1]
	v_pk_mul_f32 v[166:167], v[100:101], v[166:167]
	v_pk_mul_f32 v[168:169], v[102:103], v[168:169]
	v_pk_mul_f32 v[170:171], v[104:105], v[170:171]
	v_pk_mul_f32 v[172:173], v[106:107], v[172:173]
	v_pk_mul_f32 v[174:175], v[108:109], v[174:175]
	v_pk_mul_f32 v[176:177], v[110:111], v[176:177]
	v_pk_mul_f32 v[178:179], v[112:113], v[178:179]
	v_pk_mul_f32 v[180:181], v[114:115], v[180:181]
	v_pk_fma_f32 v[166:167], v[132:133], v[166:167], v[116:117]
	v_pk_fma_f32 v[168:169], v[134:135], v[168:169], v[118:119]
	v_pk_fma_f32 v[170:171], v[136:137], v[170:171], v[120:121]
	v_pk_fma_f32 v[172:173], v[138:139], v[172:173], v[122:123]
	v_pk_fma_f32 v[174:175], v[140:141], v[174:175], v[124:125]
	v_pk_fma_f32 v[176:177], v[142:143], v[176:177], v[126:127]
	v_pk_fma_f32 v[178:179], v[144:145], v[178:179], v[128:129]
	v_pk_fma_f32 v[180:181], v[146:147], v[180:181], v[130:131]
	v_cvt_pk_bf16_f32 v166, v166, v167
	v_cvt_pk_bf16_f32 v167, v168, v169
	v_cvt_pk_bf16_f32 v170, v170, v171
	v_cvt_pk_bf16_f32 v171, v172, v173
	v_cvt_pk_bf16_f32 v174, v174, v175
	v_cvt_pk_bf16_f32 v175, v176, v177
	v_cvt_pk_bf16_f32 v178, v178, v179
	v_cvt_pk_bf16_f32 v179, v180, v181
	global_store_dwordx2 v[184:185], v[166:167], off
	global_store_dwordx2 v[184:185], v[170:171], off offset:512
	global_store_dwordx2 v[184:185], v[174:175], off offset:1024
	global_store_dwordx2 v[184:185], v[178:179], off offset:1536
	v_lshlrev_b32_e32 v166, 16, v70
	v_and_b32_e32 v167, 0xffff0000, v70
	v_lshlrev_b32_e32 v168, 16, v71
	v_and_b32_e32 v169, 0xffff0000, v71
	v_lshlrev_b32_e32 v170, 16, v68
	v_and_b32_e32 v171, 0xffff0000, v68
	v_lshlrev_b32_e32 v172, 16, v69
	v_and_b32_e32 v173, 0xffff0000, v69
	v_lshlrev_b32_e32 v174, 16, v66
	v_and_b32_e32 v175, 0xffff0000, v66
	v_lshlrev_b32_e32 v176, 16, v67
	v_and_b32_e32 v177, 0xffff0000, v67
	v_lshlrev_b32_e32 v178, 16, v64
	v_and_b32_e32 v179, 0xffff0000, v64
	v_lshlrev_b32_e32 v180, 16, v65
	v_and_b32_e32 v181, 0xffff0000, v65
	v_lshl_add_u64 v[184:185], v[182:183], 0, s[26:27]
	v_pk_mul_f32 v[166:167], v[158:159], v[166:167] op_sel_hi:[0,1]
	v_pk_mul_f32 v[168:169], v[158:159], v[168:169] op_sel_hi:[0,1]
	v_pk_mul_f32 v[170:171], v[158:159], v[170:171] op_sel_hi:[0,1]
	v_pk_mul_f32 v[172:173], v[158:159], v[172:173] op_sel_hi:[0,1]
	v_pk_mul_f32 v[174:175], v[158:159], v[174:175] op_sel_hi:[0,1]
	v_pk_mul_f32 v[176:177], v[158:159], v[176:177] op_sel_hi:[0,1]
	v_pk_mul_f32 v[178:179], v[158:159], v[178:179] op_sel_hi:[0,1]
	v_pk_mul_f32 v[180:181], v[158:159], v[180:181] op_sel_hi:[0,1]
	v_pk_mul_f32 v[166:167], v[100:101], v[166:167]
	v_pk_mul_f32 v[168:169], v[102:103], v[168:169]
	v_pk_mul_f32 v[170:171], v[104:105], v[170:171]
	v_pk_mul_f32 v[172:173], v[106:107], v[172:173]
	v_pk_mul_f32 v[174:175], v[108:109], v[174:175]
	v_pk_mul_f32 v[176:177], v[110:111], v[176:177]
	v_pk_mul_f32 v[178:179], v[112:113], v[178:179]
	v_pk_mul_f32 v[180:181], v[114:115], v[180:181]
	v_pk_fma_f32 v[166:167], v[132:133], v[166:167], v[116:117]
	v_pk_fma_f32 v[168:169], v[134:135], v[168:169], v[118:119]
	v_pk_fma_f32 v[170:171], v[136:137], v[170:171], v[120:121]
	v_pk_fma_f32 v[172:173], v[138:139], v[172:173], v[122:123]
	v_pk_fma_f32 v[174:175], v[140:141], v[174:175], v[124:125]
	v_pk_fma_f32 v[176:177], v[142:143], v[176:177], v[126:127]
	v_pk_fma_f32 v[178:179], v[144:145], v[178:179], v[128:129]
	v_pk_fma_f32 v[180:181], v[146:147], v[180:181], v[130:131]
	v_cvt_pk_bf16_f32 v166, v166, v167
	v_cvt_pk_bf16_f32 v167, v168, v169
	v_cvt_pk_bf16_f32 v170, v170, v171
	v_cvt_pk_bf16_f32 v171, v172, v173
	v_cvt_pk_bf16_f32 v174, v174, v175
	v_cvt_pk_bf16_f32 v175, v176, v177
	v_cvt_pk_bf16_f32 v178, v178, v179
	v_cvt_pk_bf16_f32 v179, v180, v181
	global_store_dwordx2 v[184:185], v[166:167], off
	global_store_dwordx2 v[184:185], v[170:171], off offset:512
	global_store_dwordx2 v[184:185], v[174:175], off offset:1024
	global_store_dwordx2 v[184:185], v[178:179], off offset:1536
	v_lshlrev_b32_e32 v166, 16, v62
	v_and_b32_e32 v167, 0xffff0000, v62
	v_lshlrev_b32_e32 v168, 16, v63
	v_and_b32_e32 v169, 0xffff0000, v63
	v_lshlrev_b32_e32 v170, 16, v60
	v_and_b32_e32 v171, 0xffff0000, v60
	v_lshlrev_b32_e32 v172, 16, v61
	v_and_b32_e32 v173, 0xffff0000, v61
	v_lshlrev_b32_e32 v174, 16, v58
	v_and_b32_e32 v175, 0xffff0000, v58
	v_lshlrev_b32_e32 v176, 16, v59
	v_and_b32_e32 v177, 0xffff0000, v59
	v_lshlrev_b32_e32 v178, 16, v56
	v_and_b32_e32 v179, 0xffff0000, v56
	v_lshlrev_b32_e32 v180, 16, v57
	v_and_b32_e32 v181, 0xffff0000, v57
	v_lshl_add_u64 v[184:185], v[182:183], 0, s[22:23]
	v_pk_mul_f32 v[166:167], v[160:161], v[166:167] op_sel_hi:[0,1]
	v_pk_mul_f32 v[168:169], v[160:161], v[168:169] op_sel_hi:[0,1]
	v_pk_mul_f32 v[170:171], v[160:161], v[170:171] op_sel_hi:[0,1]
	v_pk_mul_f32 v[172:173], v[160:161], v[172:173] op_sel_hi:[0,1]
	v_pk_mul_f32 v[174:175], v[160:161], v[174:175] op_sel_hi:[0,1]
	v_pk_mul_f32 v[176:177], v[160:161], v[176:177] op_sel_hi:[0,1]
	v_pk_mul_f32 v[178:179], v[160:161], v[178:179] op_sel_hi:[0,1]
	v_pk_mul_f32 v[180:181], v[160:161], v[180:181] op_sel_hi:[0,1]
	v_pk_mul_f32 v[166:167], v[100:101], v[166:167]
	v_pk_mul_f32 v[168:169], v[102:103], v[168:169]
	v_pk_mul_f32 v[170:171], v[104:105], v[170:171]
	v_pk_mul_f32 v[172:173], v[106:107], v[172:173]
	v_pk_mul_f32 v[174:175], v[108:109], v[174:175]
	v_pk_mul_f32 v[176:177], v[110:111], v[176:177]
	v_pk_mul_f32 v[178:179], v[112:113], v[178:179]
	v_pk_mul_f32 v[180:181], v[114:115], v[180:181]
	v_pk_fma_f32 v[166:167], v[132:133], v[166:167], v[116:117]
	v_pk_fma_f32 v[168:169], v[134:135], v[168:169], v[118:119]
	v_pk_fma_f32 v[170:171], v[136:137], v[170:171], v[120:121]
	v_pk_fma_f32 v[172:173], v[138:139], v[172:173], v[122:123]
	v_pk_fma_f32 v[174:175], v[140:141], v[174:175], v[124:125]
	v_pk_fma_f32 v[176:177], v[142:143], v[176:177], v[126:127]
	v_pk_fma_f32 v[178:179], v[144:145], v[178:179], v[128:129]
	v_pk_fma_f32 v[180:181], v[146:147], v[180:181], v[130:131]
	v_cvt_pk_bf16_f32 v166, v166, v167
	v_cvt_pk_bf16_f32 v167, v168, v169
	v_cvt_pk_bf16_f32 v170, v170, v171
	v_cvt_pk_bf16_f32 v171, v172, v173
	v_cvt_pk_bf16_f32 v174, v174, v175
	v_cvt_pk_bf16_f32 v175, v176, v177
	v_cvt_pk_bf16_f32 v178, v178, v179
	v_cvt_pk_bf16_f32 v179, v180, v181
	global_store_dwordx2 v[184:185], v[166:167], off
	global_store_dwordx2 v[184:185], v[170:171], off offset:512
	global_store_dwordx2 v[184:185], v[174:175], off offset:1024
	global_store_dwordx2 v[184:185], v[178:179], off offset:1536
	v_lshlrev_b32_e32 v166, 16, v54
	v_and_b32_e32 v167, 0xffff0000, v54
	v_lshlrev_b32_e32 v168, 16, v55
	v_and_b32_e32 v169, 0xffff0000, v55
	v_lshlrev_b32_e32 v170, 16, v52
	v_and_b32_e32 v171, 0xffff0000, v52
	v_lshlrev_b32_e32 v172, 16, v53
	v_and_b32_e32 v173, 0xffff0000, v53
	v_lshlrev_b32_e32 v174, 16, v50
	v_and_b32_e32 v175, 0xffff0000, v50
	v_lshlrev_b32_e32 v176, 16, v51
	v_and_b32_e32 v177, 0xffff0000, v51
	v_lshlrev_b32_e32 v178, 16, v48
	v_and_b32_e32 v179, 0xffff0000, v48
	v_lshlrev_b32_e32 v180, 16, v49
	v_and_b32_e32 v181, 0xffff0000, v49
	v_lshl_add_u64 v[184:185], v[182:183], 0, s[18:19]
	v_pk_mul_f32 v[166:167], v[162:163], v[166:167] op_sel_hi:[0,1]
	v_pk_mul_f32 v[168:169], v[162:163], v[168:169] op_sel_hi:[0,1]
	v_pk_mul_f32 v[170:171], v[162:163], v[170:171] op_sel_hi:[0,1]
	v_pk_mul_f32 v[172:173], v[162:163], v[172:173] op_sel_hi:[0,1]
	v_pk_mul_f32 v[174:175], v[162:163], v[174:175] op_sel_hi:[0,1]
	v_pk_mul_f32 v[176:177], v[162:163], v[176:177] op_sel_hi:[0,1]
	v_pk_mul_f32 v[178:179], v[162:163], v[178:179] op_sel_hi:[0,1]
	v_pk_mul_f32 v[180:181], v[162:163], v[180:181] op_sel_hi:[0,1]
	v_pk_mul_f32 v[166:167], v[100:101], v[166:167]
	v_pk_mul_f32 v[168:169], v[102:103], v[168:169]
	v_pk_mul_f32 v[170:171], v[104:105], v[170:171]
	v_pk_mul_f32 v[172:173], v[106:107], v[172:173]
	v_pk_mul_f32 v[174:175], v[108:109], v[174:175]
	v_pk_mul_f32 v[176:177], v[110:111], v[176:177]
	v_pk_mul_f32 v[178:179], v[112:113], v[178:179]
	v_pk_mul_f32 v[180:181], v[114:115], v[180:181]
	v_pk_fma_f32 v[166:167], v[132:133], v[166:167], v[116:117]
	v_pk_fma_f32 v[168:169], v[134:135], v[168:169], v[118:119]
	v_pk_fma_f32 v[170:171], v[136:137], v[170:171], v[120:121]
	v_pk_fma_f32 v[172:173], v[138:139], v[172:173], v[122:123]
	v_pk_fma_f32 v[174:175], v[140:141], v[174:175], v[124:125]
	v_pk_fma_f32 v[176:177], v[142:143], v[176:177], v[126:127]
	v_pk_fma_f32 v[178:179], v[144:145], v[178:179], v[128:129]
	v_pk_fma_f32 v[180:181], v[146:147], v[180:181], v[130:131]
	v_cvt_pk_bf16_f32 v166, v166, v167
	v_cvt_pk_bf16_f32 v167, v168, v169
	v_cvt_pk_bf16_f32 v170, v170, v171
	v_cvt_pk_bf16_f32 v171, v172, v173
	v_cvt_pk_bf16_f32 v174, v174, v175
	v_cvt_pk_bf16_f32 v175, v176, v177
	v_cvt_pk_bf16_f32 v178, v178, v179
	v_cvt_pk_bf16_f32 v179, v180, v181
	global_store_dwordx2 v[184:185], v[166:167], off
	global_store_dwordx2 v[184:185], v[170:171], off offset:512
	global_store_dwordx2 v[184:185], v[174:175], off offset:1024
	global_store_dwordx2 v[184:185], v[178:179], off offset:1536
	v_lshlrev_b32_e32 v166, 16, v44
	v_and_b32_e32 v167, 0xffff0000, v44
	v_lshlrev_b32_e32 v168, 16, v45
	v_and_b32_e32 v169, 0xffff0000, v45
	v_lshlrev_b32_e32 v170, 16, v42
	v_and_b32_e32 v171, 0xffff0000, v42
	v_lshlrev_b32_e32 v172, 16, v43
	v_and_b32_e32 v173, 0xffff0000, v43
	v_lshlrev_b32_e32 v174, 16, v40
	v_and_b32_e32 v175, 0xffff0000, v40
	v_lshlrev_b32_e32 v176, 16, v41
	v_and_b32_e32 v177, 0xffff0000, v41
	v_lshlrev_b32_e32 v178, 16, v38
	v_and_b32_e32 v179, 0xffff0000, v38
	v_lshlrev_b32_e32 v180, 16, v39
	v_and_b32_e32 v181, 0xffff0000, v39
	v_lshl_add_u64 v[184:185], v[182:183], 0, s[12:13]
	v_pk_mul_f32 v[166:167], v[164:165], v[166:167] op_sel_hi:[0,1]
	v_pk_mul_f32 v[168:169], v[164:165], v[168:169] op_sel_hi:[0,1]
	v_pk_mul_f32 v[170:171], v[164:165], v[170:171] op_sel_hi:[0,1]
	v_pk_mul_f32 v[172:173], v[164:165], v[172:173] op_sel_hi:[0,1]
	v_pk_mul_f32 v[174:175], v[164:165], v[174:175] op_sel_hi:[0,1]
	v_pk_mul_f32 v[176:177], v[164:165], v[176:177] op_sel_hi:[0,1]
	v_pk_mul_f32 v[178:179], v[164:165], v[178:179] op_sel_hi:[0,1]
	v_pk_mul_f32 v[180:181], v[164:165], v[180:181] op_sel_hi:[0,1]
	v_pk_mul_f32 v[166:167], v[100:101], v[166:167]
	v_pk_mul_f32 v[168:169], v[102:103], v[168:169]
	v_pk_mul_f32 v[170:171], v[104:105], v[170:171]
	v_pk_mul_f32 v[172:173], v[106:107], v[172:173]
	v_pk_mul_f32 v[174:175], v[108:109], v[174:175]
	v_pk_mul_f32 v[176:177], v[110:111], v[176:177]
	v_pk_mul_f32 v[178:179], v[112:113], v[178:179]
	v_pk_mul_f32 v[180:181], v[114:115], v[180:181]
	v_pk_fma_f32 v[166:167], v[132:133], v[166:167], v[116:117]
	v_pk_fma_f32 v[168:169], v[134:135], v[168:169], v[118:119]
	v_pk_fma_f32 v[170:171], v[136:137], v[170:171], v[120:121]
	v_pk_fma_f32 v[172:173], v[138:139], v[172:173], v[122:123]
	v_pk_fma_f32 v[174:175], v[140:141], v[174:175], v[124:125]
	v_pk_fma_f32 v[176:177], v[142:143], v[176:177], v[126:127]
	v_pk_fma_f32 v[178:179], v[144:145], v[178:179], v[128:129]
	v_pk_fma_f32 v[180:181], v[146:147], v[180:181], v[130:131]
	v_cvt_pk_bf16_f32 v166, v166, v167
	v_cvt_pk_bf16_f32 v167, v168, v169
	v_cvt_pk_bf16_f32 v170, v170, v171
	v_cvt_pk_bf16_f32 v171, v172, v173
	v_cvt_pk_bf16_f32 v174, v174, v175
	v_cvt_pk_bf16_f32 v175, v176, v177
	v_cvt_pk_bf16_f32 v178, v178, v179
	v_cvt_pk_bf16_f32 v179, v180, v181
	global_store_dwordx2 v[184:185], v[166:167], off
	global_store_dwordx2 v[184:185], v[170:171], off offset:512
	global_store_dwordx2 v[184:185], v[174:175], off offset:1024
	global_store_dwordx2 v[184:185], v[178:179], off offset:1536
	v_mov_b32_e32 v18, s28
	v_mov_b32_e32 v19, s29
	v_add_u32_e32 v24, 0x400, v26
	v_add_u32_e32 v22, 0x800, v26
	v_add_u32_e32 v20, 0xc00, v26
	v_lshl_add_u64 v[18:19], v[18:19], 0, v[26:27]
